# design F k-loop: mid-iteration barrier moved up behind the 4th MFMA group of the even slice so the 12 LDS fills + 12 loads spread over 12 MFMA groups
# speedup vs baseline: 1.1029x; 1.0056x over previous
; template <int MODE>
; __device__ void gemm_tile2(const u16* __restrict__ X, int lda, const u16* __restrict__ W, int ldb, int K,
;                            int m0, int n0, u16* __restrict__ outb, int vbase,
;                            const float* resid, float* outf, unsigned char* smem) {
;     ...
;   G2_GLOAD(0, 0);
;   G2_GLOAD(1, 1);
;   __syncthreads();
;   G2_LSTORE(0, 0);
;   G2_GLOAD(0, 2);
;   __syncthreads();
;   for (int kt2 = 0; kt2 < nk; kt2 += 2) {
; #pragma unroll
;     for (int h = 0; h < 2; ++h) {
;       const int kt = kt2 + h;
;       const u16* st = sbase + h * G2STAGE;
;       bf16x8 fw[4], fx[4];
; #pragma unroll
;       for (int j = 0; j < 4; ++j) fw[j] = *(const bf16x8*)(st + 256 * G2S + (ww * 64 + j * 16 + l15) * G2S + fsw);
; #pragma unroll
;       for (int i = 0; i < 4; ++i) fx[i] = *(const bf16x8*)(st + (wx * 128 + i * 16 + l15) * G2S + fsw);
;       __builtin_amdgcn_sched_barrier(0);
;       __builtin_amdgcn_s_setprio(1);
; #pragma unroll
;       for (int i = 0; i < 4; ++i) {
; #pragma unroll
;         for (int j = 0; j < 4; ++j) {
;           if (MODE == 1) acc[i][j] = mfma16(fx[i], fw[j], acc[i][j]);
;           else acc[i][j] = mfma16(fw[j], fx[i], acc[i][j]);
;         }
;       }
;       __builtin_amdgcn_s_setprio(0);
;       __builtin_amdgcn_sched_barrier(0);
; #pragma unroll
;       for (int i = 0; i < 4; ++i) fx[i] = *(const bf16x8*)(st + (wx * 128 + (i + 4) * 16 + l15) * G2S + fsw);
;       __builtin_amdgcn_sched_barrier(0);
;       if (kt + 1 < nk) G2_LSTORE(1 - h, 1 - h);
;       if (kt + 3 < nk) G2_GLOAD(1 - h, kt + 3);
;       __builtin_amdgcn_sched_barrier(0);
;       __builtin_amdgcn_s_setprio(1);
; #pragma unroll
;       for (int i = 0; i < 4; ++i) {
; #pragma unroll
;         for (int j = 0; j < 4; ++j) {
;           if (MODE == 1) acc[i + 4][j] = mfma16(fx[i], fw[j], acc[i + 4][j]);
;           else acc[i + 4][j] = mfma16(fw[j], fx[i], acc[i + 4][j]);
;         }
;       }
;       __builtin_amdgcn_s_setprio(0);
;       __syncthreads();
;     }
.Lf0_loop:
	s_waitcnt lgkmcnt(3)
	v_mfma_f32_16x16x32_bf16 v[174:177], v[178:181], v[194:197], v[174:177]
	v_mfma_f32_16x16x32_bf16 v[170:173], v[182:185], v[194:197], v[170:173]
	v_mfma_f32_16x16x32_bf16 v[166:169], v[186:189], v[194:197], v[166:169]
	v_mfma_f32_16x16x32_bf16 v[162:165], v[190:193], v[194:197], v[162:165]
	ds_read_b128 v[194:197], v236 offset:4096
	ds_read_b128 v[238:241], v232 offset:16384
	s_waitcnt lgkmcnt(4)
	v_mfma_f32_16x16x32_bf16 v[158:161], v[178:181], v[198:201], v[158:161]
	v_mfma_f32_16x16x32_bf16 v[154:157], v[182:185], v[198:201], v[154:157]
	v_mfma_f32_16x16x32_bf16 v[150:153], v[186:189], v[198:201], v[150:153]
	v_mfma_f32_16x16x32_bf16 v[146:149], v[190:193], v[198:201], v[146:149]
	ds_read_b128 v[198:201], v236 offset:5120
	ds_read_b128 v[242:245], v232 offset:17408
	s_waitcnt lgkmcnt(5)
	v_mfma_f32_16x16x32_bf16 v[142:145], v[178:181], v[202:205], v[142:145]
	v_mfma_f32_16x16x32_bf16 v[138:141], v[182:185], v[202:205], v[138:141]
	v_mfma_f32_16x16x32_bf16 v[134:137], v[186:189], v[202:205], v[134:137]
	v_mfma_f32_16x16x32_bf16 v[130:133], v[190:193], v[202:205], v[130:133]
	ds_read_b128 v[202:205], v236 offset:6144
	ds_read_b128 v[246:249], v232 offset:18432
	s_waitcnt lgkmcnt(6)
	v_mfma_f32_16x16x32_bf16 v[126:129], v[178:181], v[206:209], v[126:129]
	v_mfma_f32_16x16x32_bf16 v[122:125], v[182:185], v[206:209], v[122:125]
	v_mfma_f32_16x16x32_bf16 v[118:121], v[186:189], v[206:209], v[118:121]
	v_mfma_f32_16x16x32_bf16 v[114:117], v[190:193], v[206:209], v[114:117]
	ds_read_b128 v[206:209], v236 offset:7168
	ds_read_b128 v[222:225], v232 offset:19456
	s_sub_i32 s38, s35, s6
	v_add_u32_e32 v235, s38, v235
	v_add_u32_e32 v236, s38, v236
	s_sub_i32 s38, s6, s35
	v_mad_i32_i24 v234, v221, s38, v220
	v_add_u32_e32 v234, s35, v234
	s_waitcnt lgkmcnt(1)
	s_barrier
	s_setprio 1
	v_mfma_f32_16x16x32_bf16 v[110:113], v[178:181], v[194:197], v[110:113]
	v_mfma_f32_16x16x32_bf16 v[106:109], v[182:185], v[194:197], v[106:109]
	v_mfma_f32_16x16x32_bf16 v[102:105], v[186:189], v[194:197], v[102:105]
	v_mfma_f32_16x16x32_bf16 v[98:101], v[190:193], v[194:197], v[98:101]
	ds_read_b128 v[194:197], v237
	s_waitcnt vmcnt(11)
	ds_write_b128 v234, v[2:5]
	buffer_load_dwordx4 v[2:5], v218, s[24:27], 0 offen
	v_mfma_f32_16x16x32_bf16 v[94:97], v[178:181], v[198:201], v[94:97]
	v_mfma_f32_16x16x32_bf16 v[90:93], v[182:185], v[198:201], v[90:93]
	v_mfma_f32_16x16x32_bf16 v[86:89], v[186:189], v[198:201], v[86:89]
	v_mfma_f32_16x16x32_bf16 v[82:85], v[190:193], v[198:201], v[82:85]
	ds_read_b128 v[198:201], v237 offset:1024
	s_waitcnt vmcnt(11)
	ds_write_b128 v234, v[6:9] offset:2048
	buffer_load_dwordx4 v[6:9], v219, s[24:27], 0 offen
	v_mfma_f32_16x16x32_bf16 v[78:81], v[178:181], v[202:205], v[78:81]
	v_mfma_f32_16x16x32_bf16 v[74:77], v[182:185], v[202:205], v[74:77]
	v_mfma_f32_16x16x32_bf16 v[70:73], v[186:189], v[202:205], v[70:73]
	v_mfma_f32_16x16x32_bf16 v[66:69], v[190:193], v[202:205], v[66:69]
	ds_read_b128 v[202:205], v237 offset:2048
	s_waitcnt vmcnt(11)
	ds_write_b128 v234, v[10:13] offset:4096
	buffer_load_dwordx4 v[10:13], v218, s[24:27], s27 offen
	v_mfma_f32_16x16x32_bf16 v[62:65], v[178:181], v[206:209], v[62:65]
	v_mfma_f32_16x16x32_bf16 v[58:61], v[182:185], v[206:209], v[58:61]
	v_mfma_f32_16x16x32_bf16 v[54:57], v[186:189], v[206:209], v[54:57]
	v_mfma_f32_16x16x32_bf16 v[50:53], v[190:193], v[206:209], v[50:53]
	ds_read_b128 v[206:209], v237 offset:3072
	s_waitcnt vmcnt(11)
	ds_write_b128 v234, v[14:17] offset:6144
	buffer_load_dwordx4 v[14:17], v219, s[24:27], s27 offen
	s_waitcnt lgkmcnt(7)
	v_mfma_f32_16x16x32_bf16 v[174:177], v[238:241], v[194:197], v[174:177]
	v_mfma_f32_16x16x32_bf16 v[170:173], v[242:245], v[194:197], v[170:173]
	v_mfma_f32_16x16x32_bf16 v[166:169], v[246:249], v[194:197], v[166:169]
	v_mfma_f32_16x16x32_bf16 v[162:165], v[222:225], v[194:197], v[162:165]
	ds_read_b128 v[194:197], v237 offset:4096
	s_waitcnt vmcnt(11)
	ds_write_b128 v234, v[18:21] offset:8192
	buffer_load_dwordx4 v[18:21], v218, s[24:27], s77 offen
	s_waitcnt lgkmcnt(7)
	v_mfma_f32_16x16x32_bf16 v[158:161], v[238:241], v[198:201], v[158:161]
	v_mfma_f32_16x16x32_bf16 v[154:157], v[242:245], v[198:201], v[154:157]
	v_mfma_f32_16x16x32_bf16 v[150:153], v[246:249], v[198:201], v[150:153]
	v_mfma_f32_16x16x32_bf16 v[146:149], v[222:225], v[198:201], v[146:149]
	ds_read_b128 v[198:201], v237 offset:5120
	s_waitcnt vmcnt(11)
	ds_write_b128 v234, v[22:25] offset:10240
	buffer_load_dwordx4 v[22:25], v219, s[24:27], s77 offen
	s_waitcnt lgkmcnt(7)
	v_mfma_f32_16x16x32_bf16 v[142:145], v[238:241], v[202:205], v[142:145]
	v_mfma_f32_16x16x32_bf16 v[138:141], v[242:245], v[202:205], v[138:141]
	v_mfma_f32_16x16x32_bf16 v[134:137], v[246:249], v[202:205], v[134:137]
	v_mfma_f32_16x16x32_bf16 v[130:133], v[222:225], v[202:205], v[130:133]
	ds_read_b128 v[202:205], v237 offset:6144
	s_waitcnt vmcnt(11)
	ds_write_b128 v234, v[26:29] offset:12288
	buffer_load_dwordx4 v[26:29], v218, s[24:27], s78 offen
	s_waitcnt lgkmcnt(7)
	v_mfma_f32_16x16x32_bf16 v[126:129], v[238:241], v[206:209], v[126:129]
	v_mfma_f32_16x16x32_bf16 v[122:125], v[242:245], v[206:209], v[122:125]
	v_mfma_f32_16x16x32_bf16 v[118:121], v[246:249], v[206:209], v[118:121]
	v_mfma_f32_16x16x32_bf16 v[114:117], v[222:225], v[206:209], v[114:117]
	ds_read_b128 v[206:209], v237 offset:7168
	s_sub_i32 s38, s6, s7
	v_add_u32_e32 v232, s38, v232
	v_add_u32_e32 v237, s38, v237
	s_waitcnt vmcnt(11)
	ds_write_b128 v234, v[30:33] offset:14336
	buffer_load_dwordx4 v[30:33], v219, s[24:27], s78 offen
	s_waitcnt lgkmcnt(7)
; template <int MODE>
; __device__ void gemm_tile2(const u16* __restrict__ X, int lda, const u16* __restrict__ W, int ldb, int K,
;                            int m0, int n0, u16* __restrict__ outb, int vbase,
;                            const float* resid, float* outf, unsigned char* smem) {
;     ...
;   G2_GLOAD(0, 0);
;   G2_GLOAD(1, 1);
;   __syncthreads();
;   G2_LSTORE(0, 0);
;   G2_GLOAD(0, 2);
;   __syncthreads();
;   for (int kt2 = 0; kt2 < nk; kt2 += 2) {
; #pragma unroll
;     for (int h = 0; h < 2; ++h) {
;       const int kt = kt2 + h;
;       const u16* st = sbase + h * G2STAGE;
;       bf16x8 fw[4], fx[4];
; #pragma unroll
;       for (int j = 0; j < 4; ++j) fw[j] = *(const bf16x8*)(st + 256 * G2S + (ww * 64 + j * 16 + l15) * G2S + fsw);
; #pragma unroll
;       for (int i = 0; i < 4; ++i) fx[i] = *(const bf16x8*)(st + (wx * 128 + i * 16 + l15) * G2S + fsw);
;       __builtin_amdgcn_sched_barrier(0);
;       __builtin_amdgcn_s_setprio(1);
; #pragma unroll
;       for (int i = 0; i < 4; ++i) {
; #pragma unroll
;         for (int j = 0; j < 4; ++j) {
;           if (MODE == 1) acc[i][j] = mfma16(fx[i], fw[j], acc[i][j]);
;           else acc[i][j] = mfma16(fw[j], fx[i], acc[i][j]);
;         }
;       }
;       __builtin_amdgcn_s_setprio(0);
;       __builtin_amdgcn_sched_barrier(0);
; #pragma unroll
;       for (int i = 0; i < 4; ++i) fx[i] = *(const bf16x8*)(st + (wx * 128 + (i + 4) * 16 + l15) * G2S + fsw);
;       __builtin_amdgcn_sched_barrier(0);
;       if (kt + 1 < nk) G2_LSTORE(1 - h, 1 - h);
;       if (kt + 3 < nk) G2_GLOAD(1 - h, kt + 3);
;       __builtin_amdgcn_sched_barrier(0);
;       __builtin_amdgcn_s_setprio(1);
; #pragma unroll
;       for (int i = 0; i < 4; ++i) {
; #pragma unroll
;         for (int j = 0; j < 4; ++j) {
;           if (MODE == 1) acc[i + 4][j] = mfma16(fx[i], fw[j], acc[i + 4][j]);
;           else acc[i + 4][j] = mfma16(fw[j], fx[i], acc[i + 4][j]);
;         }
;       }
;       __builtin_amdgcn_s_setprio(0);
;       __syncthreads();
;     }
	v_mfma_f32_16x16x32_bf16 v[110:113], v[238:241], v[194:197], v[110:113]
	v_mfma_f32_16x16x32_bf16 v[106:109], v[242:245], v[194:197], v[106:109]
	v_mfma_f32_16x16x32_bf16 v[102:105], v[246:249], v[194:197], v[102:105]
	v_mfma_f32_16x16x32_bf16 v[98:101], v[222:225], v[194:197], v[98:101]
	s_waitcnt vmcnt(11)
	ds_write_b128 v234, v[34:37] offset:16384
	buffer_load_dwordx4 v[34:37], v218, s[40:43], 0 offen
	s_waitcnt lgkmcnt(6)
	v_mfma_f32_16x16x32_bf16 v[94:97], v[238:241], v[198:201], v[94:97]
	v_mfma_f32_16x16x32_bf16 v[90:93], v[242:245], v[198:201], v[90:93]
	v_mfma_f32_16x16x32_bf16 v[86:89], v[246:249], v[198:201], v[86:89]
	v_mfma_f32_16x16x32_bf16 v[82:85], v[222:225], v[198:201], v[82:85]
	s_waitcnt vmcnt(11)
	ds_write_b128 v234, v[38:41] offset:18432
	buffer_load_dwordx4 v[38:41], v219, s[40:43], 0 offen
	s_waitcnt lgkmcnt(5)
	v_mfma_f32_16x16x32_bf16 v[78:81], v[238:241], v[202:205], v[78:81]
	v_mfma_f32_16x16x32_bf16 v[74:77], v[242:245], v[202:205], v[74:77]
	v_mfma_f32_16x16x32_bf16 v[70:73], v[246:249], v[202:205], v[70:73]
	v_mfma_f32_16x16x32_bf16 v[66:69], v[222:225], v[202:205], v[66:69]
	s_waitcnt vmcnt(11)
	ds_write_b128 v234, v[42:45] offset:20480
	buffer_load_dwordx4 v[42:45], v218, s[40:43], s27 offen
	s_waitcnt lgkmcnt(4)
	v_mfma_f32_16x16x32_bf16 v[62:65], v[238:241], v[206:209], v[62:65]
	v_mfma_f32_16x16x32_bf16 v[58:61], v[242:245], v[206:209], v[58:61]
	v_mfma_f32_16x16x32_bf16 v[54:57], v[246:249], v[206:209], v[54:57]
	v_mfma_f32_16x16x32_bf16 v[50:53], v[222:225], v[206:209], v[50:53]
	s_waitcnt vmcnt(11)
	ds_write_b128 v234, v[46:49] offset:22528
	buffer_load_dwordx4 v[46:49], v219, s[40:43], s27 offen
	v_add_u32_e32 v218, 0x80, v218
	v_add_u32_e32 v219, 0x80, v219
	s_waitcnt lgkmcnt(0)
	s_setprio 0
	s_barrier
	s_mov_b32 s38, s35
	s_mov_b32 s35, s7
	s_mov_b32 s7, s6
	s_mov_b32 s6, s38
	ds_read_b128 v[178:181], v235 offset:16384
	ds_read_b128 v[182:185], v235 offset:17408
	ds_read_b128 v[186:189], v235 offset:18432
	ds_read_b128 v[190:193], v235 offset:19456
	ds_read_b128 v[194:197], v236
	ds_read_b128 v[198:201], v236 offset:1024
	ds_read_b128 v[202:205], v236 offset:2048
	ds_read_b128 v[206:209], v236 offset:3072
	s_add_u32 s1, s1, 1
	s_cmp_lt_u32 s1, 14
	s_cbranch_scc1 .Lf0_loop
	s_waitcnt lgkmcnt(3)
	v_mfma_f32_16x16x32_bf16 v[174:177], v[178:181], v[194:197], v[174:177]
	v_mfma_f32_16x16x32_bf16 v[170:173], v[182:185], v[194:197], v[170:173]
	v_mfma_f32_16x16x32_bf16 v[166:169], v[186:189], v[194:197], v[166:169]
	v_mfma_f32_16x16x32_bf16 v[162:165], v[190:193], v[194:197], v[162:165]
	ds_read_b128 v[194:197], v236 offset:4096
	ds_read_b128 v[238:241], v232 offset:16384
	s_waitcnt lgkmcnt(4)
	v_mfma_f32_16x16x32_bf16 v[158:161], v[178:181], v[198:201], v[158:161]
	v_mfma_f32_16x16x32_bf16 v[154:157], v[182:185], v[198:201], v[154:157]
	v_mfma_f32_16x16x32_bf16 v[150:153], v[186:189], v[198:201], v[150:153]
	v_mfma_f32_16x16x32_bf16 v[146:149], v[190:193], v[198:201], v[146:149]
	ds_read_b128 v[198:201], v236 offset:5120
	ds_read_b128 v[242:245], v232 offset:17408
	s_waitcnt lgkmcnt(5)
	v_mfma_f32_16x16x32_bf16 v[142:145], v[178:181], v[202:205], v[142:145]
	v_mfma_f32_16x16x32_bf16 v[138:141], v[182:185], v[202:205], v[138:141]
	v_mfma_f32_16x16x32_bf16 v[134:137], v[186:189], v[202:205], v[134:137]
	v_mfma_f32_16x16x32_bf16 v[130:133], v[190:193], v[202:205], v[130:133]
	ds_read_b128 v[202:205], v236 offset:6144
	ds_read_b128 v[246:249], v232 offset:18432
	s_waitcnt lgkmcnt(6)
	v_mfma_f32_16x16x32_bf16 v[126:129], v[178:181], v[206:209], v[126:129]
	v_mfma_f32_16x16x32_bf16 v[122:125], v[182:185], v[206:209], v[122:125]
	v_mfma_f32_16x16x32_bf16 v[118:121], v[186:189], v[206:209], v[118:121]
	v_mfma_f32_16x16x32_bf16 v[114:117], v[190:193], v[206:209], v[114:117]
	ds_read_b128 v[206:209], v236 offset:7168
	ds_read_b128 v[222:225], v232 offset:19456
	s_sub_i32 s38, s35, s6
	v_add_u32_e32 v235, s38, v235
	v_add_u32_e32 v236, s38, v236
	s_sub_i32 s38, s6, s35
	v_mad_i32_i24 v234, v221, s38, v220
	v_add_u32_e32 v234, s35, v234
	s_waitcnt lgkmcnt(1)
	s_barrier
	s_setprio 1
	v_mfma_f32_16x16x32_bf16 v[110:113], v[178:181], v[194:197], v[110:113]
	v_mfma_f32_16x16x32_bf16 v[106:109], v[182:185], v[194:197], v[106:109]
	v_mfma_f32_16x16x32_bf16 v[102:105], v[186:189], v[194:197], v[102:105]
	v_mfma_f32_16x16x32_bf16 v[98:101], v[190:193], v[194:197], v[98:101]
	ds_read_b128 v[194:197], v237
	s_waitcnt vmcnt(11)
	ds_write_b128 v234, v[2:5]
	v_mfma_f32_16x16x32_bf16 v[94:97], v[178:181], v[198:201], v[94:97]
	v_mfma_f32_16x16x32_bf16 v[90:93], v[182:185], v[198:201], v[90:93]
	v_mfma_f32_16x16x32_bf16 v[86:89], v[186:189], v[198:201], v[86:89]
	v_mfma_f32_16x16x32_bf16 v[82:85], v[190:193], v[198:201], v[82:85]
	ds_read_b128 v[198:201], v237 offset:1024
	s_waitcnt vmcnt(10)
	ds_write_b128 v234, v[6:9] offset:2048
	v_mfma_f32_16x16x32_bf16 v[78:81], v[178:181], v[202:205], v[78:81]
	v_mfma_f32_16x16x32_bf16 v[74:77], v[182:185], v[202:205], v[74:77]
	v_mfma_f32_16x16x32_bf16 v[70:73], v[186:189], v[202:205], v[70:73]
	v_mfma_f32_16x16x32_bf16 v[66:69], v[190:193], v[202:205], v[66:69]
	ds_read_b128 v[202:205], v237 offset:2048
	s_waitcnt vmcnt(9)
	ds_write_b128 v234, v[10:13] offset:4096
	v_mfma_f32_16x16x32_bf16 v[62:65], v[178:181], v[206:209], v[62:65]
	v_mfma_f32_16x16x32_bf16 v[58:61], v[182:185], v[206:209], v[58:61]
	v_mfma_f32_16x16x32_bf16 v[54:57], v[186:189], v[206:209], v[54:57]
	v_mfma_f32_16x16x32_bf16 v[50:53], v[190:193], v[206:209], v[50:53]
	ds_read_b128 v[206:209], v237 offset:3072
	s_waitcnt vmcnt(8)
	ds_write_b128 v234, v[14:17] offset:6144
	s_waitcnt lgkmcnt(7)
; template <int MODE>
; __device__ void gemm_tile2(const u16* __restrict__ X, int lda, const u16* __restrict__ W, int ldb, int K,
;                            int m0, int n0, u16* __restrict__ outb, int vbase,
;                            const float* resid, float* outf, unsigned char* smem) {
;     ...
; #pragma unroll
;       for (int i = 0; i < 4; ++i) fx[i] = *(const bf16x8*)(st + (wx * 128 + (i + 4) * 16 + l15) * G2S + fsw);
;       __builtin_amdgcn_sched_barrier(0);
;       if (kt + 1 < nk) G2_LSTORE(1 - h, 1 - h);
;       if (kt + 3 < nk) G2_GLOAD(1 - h, kt + 3);
;       __builtin_amdgcn_sched_barrier(0);
;       __builtin_amdgcn_s_setprio(1);
; #pragma unroll
;       for (int i = 0; i < 4; ++i) {
; #pragma unroll
;         for (int j = 0; j < 4; ++j) {
;           if (MODE == 1) acc[i + 4][j] = mfma16(fx[i], fw[j], acc[i + 4][j]);
;           else acc[i + 4][j] = mfma16(fw[j], fx[i], acc[i + 4][j]);
;         }
;       }
;       __builtin_amdgcn_s_setprio(0);
;       __syncthreads();
;     }
;   }
	v_mfma_f32_16x16x32_bf16 v[174:177], v[238:241], v[194:197], v[174:177]
	v_mfma_f32_16x16x32_bf16 v[170:173], v[242:245], v[194:197], v[170:173]
	v_mfma_f32_16x16x32_bf16 v[166:169], v[246:249], v[194:197], v[166:169]
	v_mfma_f32_16x16x32_bf16 v[162:165], v[222:225], v[194:197], v[162:165]
	ds_read_b128 v[194:197], v237 offset:4096
	s_waitcnt vmcnt(7)
	ds_write_b128 v234, v[18:21] offset:8192
	s_waitcnt lgkmcnt(7)
	v_mfma_f32_16x16x32_bf16 v[158:161], v[238:241], v[198:201], v[158:161]
	v_mfma_f32_16x16x32_bf16 v[154:157], v[242:245], v[198:201], v[154:157]
	v_mfma_f32_16x16x32_bf16 v[150:153], v[246:249], v[198:201], v[150:153]
	v_mfma_f32_16x16x32_bf16 v[146:149], v[222:225], v[198:201], v[146:149]
	ds_read_b128 v[198:201], v237 offset:5120
	s_waitcnt vmcnt(6)
	ds_write_b128 v234, v[22:25] offset:10240
	s_waitcnt lgkmcnt(7)
	v_mfma_f32_16x16x32_bf16 v[142:145], v[238:241], v[202:205], v[142:145]
	v_mfma_f32_16x16x32_bf16 v[138:141], v[242:245], v[202:205], v[138:141]
	v_mfma_f32_16x16x32_bf16 v[134:137], v[246:249], v[202:205], v[134:137]
	v_mfma_f32_16x16x32_bf16 v[130:133], v[222:225], v[202:205], v[130:133]
	ds_read_b128 v[202:205], v237 offset:6144
	s_waitcnt vmcnt(5)
	ds_write_b128 v234, v[26:29] offset:12288
	s_waitcnt lgkmcnt(7)
	v_mfma_f32_16x16x32_bf16 v[126:129], v[238:241], v[206:209], v[126:129]
	v_mfma_f32_16x16x32_bf16 v[122:125], v[242:245], v[206:209], v[122:125]
	v_mfma_f32_16x16x32_bf16 v[118:121], v[246:249], v[206:209], v[118:121]
	v_mfma_f32_16x16x32_bf16 v[114:117], v[222:225], v[206:209], v[114:117]
	ds_read_b128 v[206:209], v237 offset:7168
	s_sub_i32 s38, s6, s7
	v_add_u32_e32 v232, s38, v232
	v_add_u32_e32 v237, s38, v237
	s_waitcnt vmcnt(4)
	ds_write_b128 v234, v[30:33] offset:14336
	s_waitcnt lgkmcnt(7)
	v_mfma_f32_16x16x32_bf16 v[110:113], v[238:241], v[194:197], v[110:113]
	v_mfma_f32_16x16x32_bf16 v[106:109], v[242:245], v[194:197], v[106:109]
	v_mfma_f32_16x16x32_bf16 v[102:105], v[246:249], v[194:197], v[102:105]
	v_mfma_f32_16x16x32_bf16 v[98:101], v[222:225], v[194:197], v[98:101]
	s_waitcnt vmcnt(3)
	ds_write_b128 v234, v[34:37] offset:16384
	s_waitcnt lgkmcnt(6)
	v_mfma_f32_16x16x32_bf16 v[94:97], v[238:241], v[198:201], v[94:97]
	v_mfma_f32_16x16x32_bf16 v[90:93], v[242:245], v[198:201], v[90:93]
	v_mfma_f32_16x16x32_bf16 v[86:89], v[246:249], v[198:201], v[86:89]
	v_mfma_f32_16x16x32_bf16 v[82:85], v[222:225], v[198:201], v[82:85]
	s_waitcnt vmcnt(2)
	ds_write_b128 v234, v[38:41] offset:18432
	s_waitcnt lgkmcnt(5)
	v_mfma_f32_16x16x32_bf16 v[78:81], v[238:241], v[202:205], v[78:81]
	v_mfma_f32_16x16x32_bf16 v[74:77], v[242:245], v[202:205], v[74:77]
	v_mfma_f32_16x16x32_bf16 v[70:73], v[246:249], v[202:205], v[70:73]
	v_mfma_f32_16x16x32_bf16 v[66:69], v[222:225], v[202:205], v[66:69]
	s_waitcnt vmcnt(1)
	ds_write_b128 v234, v[42:45] offset:20480
	s_waitcnt lgkmcnt(4)
	v_mfma_f32_16x16x32_bf16 v[62:65], v[238:241], v[206:209], v[62:65]
	v_mfma_f32_16x16x32_bf16 v[58:61], v[242:245], v[206:209], v[58:61]
	v_mfma_f32_16x16x32_bf16 v[54:57], v[246:249], v[206:209], v[54:57]
	v_mfma_f32_16x16x32_bf16 v[50:53], v[222:225], v[206:209], v[50:53]
	s_waitcnt vmcnt(0)
	ds_write_b128 v234, v[46:49] offset:22528
	s_waitcnt lgkmcnt(0)
	s_setprio 0
	s_barrier
	s_mov_b32 s38, s35
	s_mov_b32 s35, s7
	s_mov_b32 s7, s6
	s_mov_b32 s6, s38
	ds_read_b128 v[178:181], v235 offset:16384
	ds_read_b128 v[182:185], v235 offset:17408
	ds_read_b128 v[186:189], v235 offset:18432
	ds_read_b128 v[190:193], v235 offset:19456
	ds_read_b128 v[194:197], v236
	ds_read_b128 v[198:201], v236 offset:1024
	ds_read_b128 v[202:205], v236 offset:2048
	ds_read_b128 v[206:209], v236 offset:3072
	s_waitcnt lgkmcnt(3)
	v_mfma_f32_16x16x32_bf16 v[174:177], v[178:181], v[194:197], v[174:177]
	v_mfma_f32_16x16x32_bf16 v[170:173], v[182:185], v[194:197], v[170:173]
	v_mfma_f32_16x16x32_bf16 v[166:169], v[186:189], v[194:197], v[166:169]
	v_mfma_f32_16x16x32_bf16 v[162:165], v[190:193], v[194:197], v[162:165]
	ds_read_b128 v[194:197], v236 offset:4096
	ds_read_b128 v[238:241], v232 offset:16384
	s_waitcnt lgkmcnt(4)
	v_mfma_f32_16x16x32_bf16 v[158:161], v[178:181], v[198:201], v[158:161]
	v_mfma_f32_16x16x32_bf16 v[154:157], v[182:185], v[198:201], v[154:157]
	v_mfma_f32_16x16x32_bf16 v[150:153], v[186:189], v[198:201], v[150:153]
	v_mfma_f32_16x16x32_bf16 v[146:149], v[190:193], v[198:201], v[146:149]
	ds_read_b128 v[198:201], v236 offset:5120
	ds_read_b128 v[242:245], v232 offset:17408
	s_waitcnt lgkmcnt(5)
	v_mfma_f32_16x16x32_bf16 v[142:145], v[178:181], v[202:205], v[142:145]
	v_mfma_f32_16x16x32_bf16 v[138:141], v[182:185], v[202:205], v[138:141]
	v_mfma_f32_16x16x32_bf16 v[134:137], v[186:189], v[202:205], v[134:137]
	v_mfma_f32_16x16x32_bf16 v[130:133], v[190:193], v[202:205], v[130:133]
	ds_read_b128 v[202:205], v236 offset:6144
	ds_read_b128 v[246:249], v232 offset:18432
	s_waitcnt lgkmcnt(6)
	v_mfma_f32_16x16x32_bf16 v[126:129], v[178:181], v[206:209], v[126:129]
	v_mfma_f32_16x16x32_bf16 v[122:125], v[182:185], v[206:209], v[122:125]
	v_mfma_f32_16x16x32_bf16 v[118:121], v[186:189], v[206:209], v[118:121]
	v_mfma_f32_16x16x32_bf16 v[114:117], v[190:193], v[206:209], v[114:117]
	ds_read_b128 v[206:209], v236 offset:7168
	ds_read_b128 v[222:225], v232 offset:19456
	s_sub_i32 s38, s35, s6
	v_add_u32_e32 v235, s38, v235
	v_add_u32_e32 v236, s38, v236
	s_waitcnt lgkmcnt(1)
	s_barrier
; template <int MODE>
; __device__ void gemm_tile2(const u16* __restrict__ X, int lda, const u16* __restrict__ W, int ldb, int K,
;                            int m0, int n0, u16* __restrict__ outb, int vbase,
;                            const float* resid, float* outf, unsigned char* smem) {
;     ...
;   for (int kt2 = 0; kt2 < nk; kt2 += 2) {
; #pragma unroll
;     for (int h = 0; h < 2; ++h) {
;       const int kt = kt2 + h;
;       const u16* st = sbase + h * G2STAGE;
;       bf16x8 fw[4], fx[4];
; #pragma unroll
;       for (int j = 0; j < 4; ++j) fw[j] = *(const bf16x8*)(st + 256 * G2S + (ww * 64 + j * 16 + l15) * G2S + fsw);
; #pragma unroll
;       for (int i = 0; i < 4; ++i) fx[i] = *(const bf16x8*)(st + (wx * 128 + i * 16 + l15) * G2S + fsw);
;       __builtin_amdgcn_sched_barrier(0);
;       __builtin_amdgcn_s_setprio(1);
; #pragma unroll
;       for (int i = 0; i < 4; ++i) {
; #pragma unroll
;         for (int j = 0; j < 4; ++j) {
;           if (MODE == 1) acc[i][j] = mfma16(fx[i], fw[j], acc[i][j]);
;           else acc[i][j] = mfma16(fw[j], fx[i], acc[i][j]);
;         }
;       }
;       __builtin_amdgcn_s_setprio(0);
;       __builtin_amdgcn_sched_barrier(0);
; #pragma unroll
;       for (int i = 0; i < 4; ++i) fx[i] = *(const bf16x8*)(st + (wx * 128 + (i + 4) * 16 + l15) * G2S + fsw);
;       __builtin_amdgcn_sched_barrier(0);
;       if (kt + 1 < nk) G2_LSTORE(1 - h, 1 - h);
;       if (kt + 3 < nk) G2_GLOAD(1 - h, kt + 3);
;       __builtin_amdgcn_sched_barrier(0);
;       __builtin_amdgcn_s_setprio(1);
; #pragma unroll
;       for (int i = 0; i < 4; ++i) {
; #pragma unroll
;         for (int j = 0; j < 4; ++j) {
;           if (MODE == 1) acc[i + 4][j] = mfma16(fx[i], fw[j], acc[i + 4][j]);
;           else acc[i + 4][j] = mfma16(fw[j], fx[i], acc[i + 4][j]);
;         }
;       }
;       __builtin_amdgcn_s_setprio(0);
;       __syncthreads();
;     }
;   }
	s_setprio 1
	v_mfma_f32_16x16x32_bf16 v[110:113], v[178:181], v[194:197], v[110:113]
	v_mfma_f32_16x16x32_bf16 v[106:109], v[182:185], v[194:197], v[106:109]
	v_mfma_f32_16x16x32_bf16 v[102:105], v[186:189], v[194:197], v[102:105]
	v_mfma_f32_16x16x32_bf16 v[98:101], v[190:193], v[194:197], v[98:101]
	ds_read_b128 v[194:197], v237
	v_mfma_f32_16x16x32_bf16 v[94:97], v[178:181], v[198:201], v[94:97]
	v_mfma_f32_16x16x32_bf16 v[90:93], v[182:185], v[198:201], v[90:93]
	v_mfma_f32_16x16x32_bf16 v[86:89], v[186:189], v[198:201], v[86:89]
	v_mfma_f32_16x16x32_bf16 v[82:85], v[190:193], v[198:201], v[82:85]
	ds_read_b128 v[198:201], v237 offset:1024
	v_mfma_f32_16x16x32_bf16 v[78:81], v[178:181], v[202:205], v[78:81]
	v_mfma_f32_16x16x32_bf16 v[74:77], v[182:185], v[202:205], v[74:77]
	v_mfma_f32_16x16x32_bf16 v[70:73], v[186:189], v[202:205], v[70:73]
	v_mfma_f32_16x16x32_bf16 v[66:69], v[190:193], v[202:205], v[66:69]
	ds_read_b128 v[202:205], v237 offset:2048
	v_mfma_f32_16x16x32_bf16 v[62:65], v[178:181], v[206:209], v[62:65]
	v_mfma_f32_16x16x32_bf16 v[58:61], v[182:185], v[206:209], v[58:61]
	v_mfma_f32_16x16x32_bf16 v[54:57], v[186:189], v[206:209], v[54:57]
	v_mfma_f32_16x16x32_bf16 v[50:53], v[190:193], v[206:209], v[50:53]
	ds_read_b128 v[206:209], v237 offset:3072
	s_waitcnt lgkmcnt(3)
	v_mfma_f32_16x16x32_bf16 v[174:177], v[238:241], v[194:197], v[174:177]
	v_mfma_f32_16x16x32_bf16 v[170:173], v[242:245], v[194:197], v[170:173]
	v_mfma_f32_16x16x32_bf16 v[166:169], v[246:249], v[194:197], v[166:169]
	v_mfma_f32_16x16x32_bf16 v[162:165], v[222:225], v[194:197], v[162:165]
	ds_read_b128 v[194:197], v237 offset:4096
	s_waitcnt lgkmcnt(3)
	v_mfma_f32_16x16x32_bf16 v[158:161], v[238:241], v[198:201], v[158:161]
	v_mfma_f32_16x16x32_bf16 v[154:157], v[242:245], v[198:201], v[154:157]
	v_mfma_f32_16x16x32_bf16 v[150:153], v[246:249], v[198:201], v[150:153]
	v_mfma_f32_16x16x32_bf16 v[146:149], v[222:225], v[198:201], v[146:149]
	ds_read_b128 v[198:201], v237 offset:5120
	s_waitcnt lgkmcnt(3)
	v_mfma_f32_16x16x32_bf16 v[142:145], v[238:241], v[202:205], v[142:145]
	v_mfma_f32_16x16x32_bf16 v[138:141], v[242:245], v[202:205], v[138:141]
	v_mfma_f32_16x16x32_bf16 v[134:137], v[246:249], v[202:205], v[134:137]
	v_mfma_f32_16x16x32_bf16 v[130:133], v[222:225], v[202:205], v[130:133]
	ds_read_b128 v[202:205], v237 offset:6144
	s_waitcnt lgkmcnt(3)
	v_mfma_f32_16x16x32_bf16 v[126:129], v[238:241], v[206:209], v[126:129]
	v_mfma_f32_16x16x32_bf16 v[122:125], v[242:245], v[206:209], v[122:125]
	v_mfma_f32_16x16x32_bf16 v[118:121], v[246:249], v[206:209], v[118:121]
	v_mfma_f32_16x16x32_bf16 v[114:117], v[222:225], v[206:209], v[114:117]
	ds_read_b128 v[206:209], v237 offset:7168
	s_sub_i32 s38, s6, s7
	v_add_u32_e32 v232, s38, v232
	v_add_u32_e32 v237, s38, v237
	s_waitcnt lgkmcnt(3)
	v_mfma_f32_16x16x32_bf16 v[110:113], v[238:241], v[194:197], v[110:113]
	v_mfma_f32_16x16x32_bf16 v[106:109], v[242:245], v[194:197], v[106:109]
	v_mfma_f32_16x16x32_bf16 v[102:105], v[246:249], v[194:197], v[102:105]
	v_mfma_f32_16x16x32_bf16 v[98:101], v[222:225], v[194:197], v[98:101]
	s_waitcnt lgkmcnt(2)
	v_mfma_f32_16x16x32_bf16 v[94:97], v[238:241], v[198:201], v[94:97]
	v_mfma_f32_16x16x32_bf16 v[90:93], v[242:245], v[198:201], v[90:93]
	v_mfma_f32_16x16x32_bf16 v[86:89], v[246:249], v[198:201], v[86:89]
	v_mfma_f32_16x16x32_bf16 v[82:85], v[222:225], v[198:201], v[82:85]
	s_waitcnt lgkmcnt(1)
	v_mfma_f32_16x16x32_bf16 v[78:81], v[238:241], v[202:205], v[78:81]
	v_mfma_f32_16x16x32_bf16 v[74:77], v[242:245], v[202:205], v[74:77]
	v_mfma_f32_16x16x32_bf16 v[70:73], v[246:249], v[202:205], v[70:73]
	v_mfma_f32_16x16x32_bf16 v[66:69], v[222:225], v[202:205], v[66:69]
	s_waitcnt lgkmcnt(0)
	v_mfma_f32_16x16x32_bf16 v[62:65], v[238:241], v[206:209], v[62:65]
	v_mfma_f32_16x16x32_bf16 v[58:61], v[242:245], v[206:209], v[58:61]
	v_mfma_f32_16x16x32_bf16 v[54:57], v[246:249], v[206:209], v[54:57]
	v_mfma_f32_16x16x32_bf16 v[50:53], v[222:225], v[206:209], v[50:53]
	s_setprio 0
	s_barrier
	s_mov_b32 s38, s35
	s_mov_b32 s35, s7
	s_mov_b32 s7, s6
	s_mov_b32 s6, s38
	s_nop 7

; template <int MODE>
; __device__ void gemm_tile2(const u16* __restrict__ X, int lda, const u16* __restrict__ W, int ldb, int K,
;                            int m0, int n0, u16* __restrict__ outb, int vbase,
;                            const float* resid, float* outf, unsigned char* smem) {
;     ...
;   G2_GLOAD(0, 0);
;   G2_GLOAD(1, 1);
;   __syncthreads();
;   G2_LSTORE(0, 0);
;   G2_GLOAD(0, 2);
;   __syncthreads();
;   for (int kt2 = 0; kt2 < nk; kt2 += 2) {
; #pragma unroll
;     for (int h = 0; h < 2; ++h) {
;       const int kt = kt2 + h;
;       const u16* st = sbase + h * G2STAGE;
;       bf16x8 fw[4], fx[4];
; #pragma unroll
;       for (int j = 0; j < 4; ++j) fw[j] = *(const bf16x8*)(st + 256 * G2S + (ww * 64 + j * 16 + l15) * G2S + fsw);
; #pragma unroll
;       for (int i = 0; i < 4; ++i) fx[i] = *(const bf16x8*)(st + (wx * 128 + i * 16 + l15) * G2S + fsw);
;       __builtin_amdgcn_sched_barrier(0);
;       __builtin_amdgcn_s_setprio(1);
; #pragma unroll
;       for (int i = 0; i < 4; ++i) {
; #pragma unroll
;         for (int j = 0; j < 4; ++j) {
;           if (MODE == 1) acc[i][j] = mfma16(fx[i], fw[j], acc[i][j]);
;           else acc[i][j] = mfma16(fw[j], fx[i], acc[i][j]);
;         }
;       }
;       __builtin_amdgcn_s_setprio(0);
;       __builtin_amdgcn_sched_barrier(0);
; #pragma unroll
;       for (int i = 0; i < 4; ++i) fx[i] = *(const bf16x8*)(st + (wx * 128 + (i + 4) * 16 + l15) * G2S + fsw);
;       __builtin_amdgcn_sched_barrier(0);
;       if (kt + 1 < nk) G2_LSTORE(1 - h, 1 - h);
;       if (kt + 3 < nk) G2_GLOAD(1 - h, kt + 3);
;       __builtin_amdgcn_sched_barrier(0);
;       __builtin_amdgcn_s_setprio(1);
; #pragma unroll
;       for (int i = 0; i < 4; ++i) {
; #pragma unroll
;         for (int j = 0; j < 4; ++j) {
;           if (MODE == 1) acc[i + 4][j] = mfma16(fx[i], fw[j], acc[i + 4][j]);
;           else acc[i + 4][j] = mfma16(fw[j], fx[i], acc[i + 4][j]);
;         }
;       }
;       __builtin_amdgcn_s_setprio(0);
;       __syncthreads();
;     }
;   }
.Lf1_loop:
	s_waitcnt lgkmcnt(3)
	v_mfma_f32_16x16x32_bf16 v[174:177], v[194:197], v[178:181], v[174:177]
	v_mfma_f32_16x16x32_bf16 v[170:173], v[194:197], v[182:185], v[170:173]
	v_mfma_f32_16x16x32_bf16 v[166:169], v[194:197], v[186:189], v[166:169]
	v_mfma_f32_16x16x32_bf16 v[162:165], v[194:197], v[190:193], v[162:165]
	ds_read_b128 v[194:197], v237 offset:4096
	ds_read_b128 v[238:241], v233 offset:16384
	s_waitcnt lgkmcnt(4)
	v_mfma_f32_16x16x32_bf16 v[158:161], v[198:201], v[178:181], v[158:161]
	v_mfma_f32_16x16x32_bf16 v[154:157], v[198:201], v[182:185], v[154:157]
	v_mfma_f32_16x16x32_bf16 v[150:153], v[198:201], v[186:189], v[150:153]
	v_mfma_f32_16x16x32_bf16 v[146:149], v[198:201], v[190:193], v[146:149]
	ds_read_b128 v[198:201], v237 offset:5120
	ds_read_b128 v[242:245], v233 offset:17408
	s_waitcnt lgkmcnt(5)
	v_mfma_f32_16x16x32_bf16 v[142:145], v[202:205], v[178:181], v[142:145]
	v_mfma_f32_16x16x32_bf16 v[138:141], v[202:205], v[182:185], v[138:141]
	v_mfma_f32_16x16x32_bf16 v[134:137], v[202:205], v[186:189], v[134:137]
	v_mfma_f32_16x16x32_bf16 v[130:133], v[202:205], v[190:193], v[130:133]
	ds_read_b128 v[202:205], v237 offset:6144
	ds_read_b128 v[246:249], v233 offset:18432
	s_waitcnt lgkmcnt(6)
	v_mfma_f32_16x16x32_bf16 v[126:129], v[206:209], v[178:181], v[126:129]
	v_mfma_f32_16x16x32_bf16 v[122:125], v[206:209], v[182:185], v[122:125]
	v_mfma_f32_16x16x32_bf16 v[118:121], v[206:209], v[186:189], v[118:121]
	v_mfma_f32_16x16x32_bf16 v[114:117], v[206:209], v[190:193], v[114:117]
	ds_read_b128 v[206:209], v237 offset:7168
	ds_read_b128 v[222:225], v233 offset:19456
	s_sub_i32 s35, s7, s1
	v_add_u32_e32 v236, s35, v236
	v_add_u32_e32 v237, s35, v237
	s_sub_i32 s35, s1, s7
	v_mad_i32_i24 v235, v221, s35, v220
	v_add_u32_e32 v235, s7, v235
	s_waitcnt lgkmcnt(1)
	s_barrier
	s_setprio 1
	v_mfma_f32_16x16x32_bf16 v[110:113], v[194:197], v[178:181], v[110:113]
	v_mfma_f32_16x16x32_bf16 v[106:109], v[194:197], v[182:185], v[106:109]
	v_mfma_f32_16x16x32_bf16 v[102:105], v[194:197], v[186:189], v[102:105]
	v_mfma_f32_16x16x32_bf16 v[98:101], v[194:197], v[190:193], v[98:101]
	ds_read_b128 v[194:197], v232
	s_waitcnt vmcnt(11)
	ds_write_b128 v235, v[2:5]
	buffer_load_dwordx4 v[2:5], v218, s[24:27], 0 offen
	v_mfma_f32_16x16x32_bf16 v[94:97], v[198:201], v[178:181], v[94:97]
	v_mfma_f32_16x16x32_bf16 v[90:93], v[198:201], v[182:185], v[90:93]
	v_mfma_f32_16x16x32_bf16 v[86:89], v[198:201], v[186:189], v[86:89]
	v_mfma_f32_16x16x32_bf16 v[82:85], v[198:201], v[190:193], v[82:85]
	ds_read_b128 v[198:201], v232 offset:1024
	s_waitcnt vmcnt(11)
	ds_write_b128 v235, v[6:9] offset:2048
	buffer_load_dwordx4 v[6:9], v219, s[24:27], 0 offen
	v_mfma_f32_16x16x32_bf16 v[78:81], v[202:205], v[178:181], v[78:81]
	v_mfma_f32_16x16x32_bf16 v[74:77], v[202:205], v[182:185], v[74:77]
	v_mfma_f32_16x16x32_bf16 v[70:73], v[202:205], v[186:189], v[70:73]
	v_mfma_f32_16x16x32_bf16 v[66:69], v[202:205], v[190:193], v[66:69]
	ds_read_b128 v[202:205], v232 offset:2048
	s_waitcnt vmcnt(11)
	ds_write_b128 v235, v[10:13] offset:4096
	buffer_load_dwordx4 v[10:13], v218, s[24:27], s27 offen
	v_mfma_f32_16x16x32_bf16 v[62:65], v[206:209], v[178:181], v[62:65]
	v_mfma_f32_16x16x32_bf16 v[58:61], v[206:209], v[182:185], v[58:61]
	v_mfma_f32_16x16x32_bf16 v[54:57], v[206:209], v[186:189], v[54:57]
	v_mfma_f32_16x16x32_bf16 v[50:53], v[206:209], v[190:193], v[50:53]
	ds_read_b128 v[206:209], v232 offset:3072
	s_waitcnt vmcnt(11)
	ds_write_b128 v235, v[14:17] offset:6144
	buffer_load_dwordx4 v[14:17], v219, s[24:27], s27 offen
	s_waitcnt lgkmcnt(7)
	v_mfma_f32_16x16x32_bf16 v[174:177], v[194:197], v[238:241], v[174:177]
	v_mfma_f32_16x16x32_bf16 v[170:173], v[194:197], v[242:245], v[170:173]
	v_mfma_f32_16x16x32_bf16 v[166:169], v[194:197], v[246:249], v[166:169]
	v_mfma_f32_16x16x32_bf16 v[162:165], v[194:197], v[222:225], v[162:165]
	ds_read_b128 v[194:197], v232 offset:4096
	s_waitcnt vmcnt(11)
	ds_write_b128 v235, v[18:21] offset:8192
	buffer_load_dwordx4 v[18:21], v218, s[24:27], s77 offen
	s_waitcnt lgkmcnt(7)
	v_mfma_f32_16x16x32_bf16 v[158:161], v[198:201], v[238:241], v[158:161]
	v_mfma_f32_16x16x32_bf16 v[154:157], v[198:201], v[242:245], v[154:157]
	v_mfma_f32_16x16x32_bf16 v[150:153], v[198:201], v[246:249], v[150:153]
	v_mfma_f32_16x16x32_bf16 v[146:149], v[198:201], v[222:225], v[146:149]
	ds_read_b128 v[198:201], v232 offset:5120
	s_waitcnt vmcnt(11)
	ds_write_b128 v235, v[22:25] offset:10240
	buffer_load_dwordx4 v[22:25], v219, s[24:27], s77 offen
	s_waitcnt lgkmcnt(7)
	v_mfma_f32_16x16x32_bf16 v[142:145], v[202:205], v[238:241], v[142:145]
	v_mfma_f32_16x16x32_bf16 v[138:141], v[202:205], v[242:245], v[138:141]
	v_mfma_f32_16x16x32_bf16 v[134:137], v[202:205], v[246:249], v[134:137]
	v_mfma_f32_16x16x32_bf16 v[130:133], v[202:205], v[222:225], v[130:133]
	ds_read_b128 v[202:205], v232 offset:6144
	s_waitcnt vmcnt(11)
	ds_write_b128 v235, v[26:29] offset:12288
	buffer_load_dwordx4 v[26:29], v218, s[24:27], s78 offen
	s_waitcnt lgkmcnt(7)
	v_mfma_f32_16x16x32_bf16 v[126:129], v[206:209], v[238:241], v[126:129]
	v_mfma_f32_16x16x32_bf16 v[122:125], v[206:209], v[242:245], v[122:125]
	v_mfma_f32_16x16x32_bf16 v[118:121], v[206:209], v[246:249], v[118:121]
	v_mfma_f32_16x16x32_bf16 v[114:117], v[206:209], v[222:225], v[114:117]
	ds_read_b128 v[206:209], v232 offset:7168
	s_sub_i32 s35, s1, s6
	v_add_u32_e32 v233, s35, v233
	v_add_u32_e32 v232, s35, v232
	s_waitcnt vmcnt(11)
	ds_write_b128 v235, v[30:33] offset:14336
	buffer_load_dwordx4 v[30:33], v219, s[24:27], s78 offen
	s_waitcnt lgkmcnt(7)
; template <int MODE>
; __device__ void gemm_tile2(const u16* __restrict__ X, int lda, const u16* __restrict__ W, int ldb, int K,
;                            int m0, int n0, u16* __restrict__ outb, int vbase,
;                            const float* resid, float* outf, unsigned char* smem) {
;     ...
;   G2_GLOAD(0, 0);
;   G2_GLOAD(1, 1);
;   __syncthreads();
;   G2_LSTORE(0, 0);
;   G2_GLOAD(0, 2);
;   __syncthreads();
;   for (int kt2 = 0; kt2 < nk; kt2 += 2) {
; #pragma unroll
;     for (int h = 0; h < 2; ++h) {
;       const int kt = kt2 + h;
;       const u16* st = sbase + h * G2STAGE;
;       bf16x8 fw[4], fx[4];
; #pragma unroll
;       for (int j = 0; j < 4; ++j) fw[j] = *(const bf16x8*)(st + 256 * G2S + (ww * 64 + j * 16 + l15) * G2S + fsw);
; #pragma unroll
;       for (int i = 0; i < 4; ++i) fx[i] = *(const bf16x8*)(st + (wx * 128 + i * 16 + l15) * G2S + fsw);
;       __builtin_amdgcn_sched_barrier(0);
;       __builtin_amdgcn_s_setprio(1);
; #pragma unroll
;       for (int i = 0; i < 4; ++i) {
; #pragma unroll
;         for (int j = 0; j < 4; ++j) {
;           if (MODE == 1) acc[i][j] = mfma16(fx[i], fw[j], acc[i][j]);
;           else acc[i][j] = mfma16(fw[j], fx[i], acc[i][j]);
;         }
;       }
;       __builtin_amdgcn_s_setprio(0);
;       __builtin_amdgcn_sched_barrier(0);
; #pragma unroll
;       for (int i = 0; i < 4; ++i) fx[i] = *(const bf16x8*)(st + (wx * 128 + (i + 4) * 16 + l15) * G2S + fsw);
;       __builtin_amdgcn_sched_barrier(0);
;       if (kt + 1 < nk) G2_LSTORE(1 - h, 1 - h);
;       if (kt + 3 < nk) G2_GLOAD(1 - h, kt + 3);
;       __builtin_amdgcn_sched_barrier(0);
;       __builtin_amdgcn_s_setprio(1);
; #pragma unroll
;       for (int i = 0; i < 4; ++i) {
; #pragma unroll
;         for (int j = 0; j < 4; ++j) {
;           if (MODE == 1) acc[i + 4][j] = mfma16(fx[i], fw[j], acc[i + 4][j]);
;           else acc[i + 4][j] = mfma16(fw[j], fx[i], acc[i + 4][j]);
;         }
;       }
;       __builtin_amdgcn_s_setprio(0);
;       __syncthreads();
;     }
;   }
	v_mfma_f32_16x16x32_bf16 v[110:113], v[194:197], v[238:241], v[110:113]
	v_mfma_f32_16x16x32_bf16 v[106:109], v[194:197], v[242:245], v[106:109]
	v_mfma_f32_16x16x32_bf16 v[102:105], v[194:197], v[246:249], v[102:105]
	v_mfma_f32_16x16x32_bf16 v[98:101], v[194:197], v[222:225], v[98:101]
	s_waitcnt vmcnt(11)
	ds_write_b128 v235, v[34:37] offset:16384
	buffer_load_dwordx4 v[34:37], v218, s[40:43], 0 offen
	s_waitcnt lgkmcnt(6)
	v_mfma_f32_16x16x32_bf16 v[94:97], v[198:201], v[238:241], v[94:97]
	v_mfma_f32_16x16x32_bf16 v[90:93], v[198:201], v[242:245], v[90:93]
	v_mfma_f32_16x16x32_bf16 v[86:89], v[198:201], v[246:249], v[86:89]
	v_mfma_f32_16x16x32_bf16 v[82:85], v[198:201], v[222:225], v[82:85]
	s_waitcnt vmcnt(11)
	ds_write_b128 v235, v[38:41] offset:18432
	buffer_load_dwordx4 v[38:41], v219, s[40:43], 0 offen
	s_waitcnt lgkmcnt(5)
	v_mfma_f32_16x16x32_bf16 v[78:81], v[202:205], v[238:241], v[78:81]
	v_mfma_f32_16x16x32_bf16 v[74:77], v[202:205], v[242:245], v[74:77]
	v_mfma_f32_16x16x32_bf16 v[70:73], v[202:205], v[246:249], v[70:73]
	v_mfma_f32_16x16x32_bf16 v[66:69], v[202:205], v[222:225], v[66:69]
	s_waitcnt vmcnt(11)
	ds_write_b128 v235, v[42:45] offset:20480
	buffer_load_dwordx4 v[42:45], v218, s[40:43], s27 offen
	s_waitcnt lgkmcnt(4)
	v_mfma_f32_16x16x32_bf16 v[62:65], v[206:209], v[238:241], v[62:65]
	v_mfma_f32_16x16x32_bf16 v[58:61], v[206:209], v[242:245], v[58:61]
	v_mfma_f32_16x16x32_bf16 v[54:57], v[206:209], v[246:249], v[54:57]
	v_mfma_f32_16x16x32_bf16 v[50:53], v[206:209], v[222:225], v[50:53]
	s_waitcnt vmcnt(11)
	ds_write_b128 v235, v[46:49] offset:22528
	buffer_load_dwordx4 v[46:49], v219, s[40:43], s27 offen
	v_add_u32_e32 v218, 0x80, v218
	v_add_u32_e32 v219, 0x80, v219
	s_waitcnt lgkmcnt(0)
	s_setprio 0
	s_barrier
	s_mov_b32 s35, s7
	s_mov_b32 s7, s6
	s_mov_b32 s6, s1
	s_mov_b32 s1, s35
	ds_read_b128 v[178:181], v236 offset:16384
	ds_read_b128 v[182:185], v236 offset:17408
	ds_read_b128 v[186:189], v236 offset:18432
	ds_read_b128 v[190:193], v236 offset:19456
	ds_read_b128 v[194:197], v237
	ds_read_b128 v[198:201], v237 offset:1024
	ds_read_b128 v[202:205], v237 offset:2048
	ds_read_b128 v[206:209], v237 offset:3072
	s_add_u32 s0, s0, 1
	s_cmp_lt_u32 s0, 14
	s_cbranch_scc1 .Lf1_loop
	s_waitcnt lgkmcnt(3)
	v_mfma_f32_16x16x32_bf16 v[174:177], v[194:197], v[178:181], v[174:177]
	v_mfma_f32_16x16x32_bf16 v[170:173], v[194:197], v[182:185], v[170:173]
	v_mfma_f32_16x16x32_bf16 v[166:169], v[194:197], v[186:189], v[166:169]
	v_mfma_f32_16x16x32_bf16 v[162:165], v[194:197], v[190:193], v[162:165]
	ds_read_b128 v[194:197], v237 offset:4096
	ds_read_b128 v[238:241], v233 offset:16384
	s_waitcnt lgkmcnt(4)
	v_mfma_f32_16x16x32_bf16 v[158:161], v[198:201], v[178:181], v[158:161]
	v_mfma_f32_16x16x32_bf16 v[154:157], v[198:201], v[182:185], v[154:157]
	v_mfma_f32_16x16x32_bf16 v[150:153], v[198:201], v[186:189], v[150:153]
	v_mfma_f32_16x16x32_bf16 v[146:149], v[198:201], v[190:193], v[146:149]
	ds_read_b128 v[198:201], v237 offset:5120
	ds_read_b128 v[242:245], v233 offset:17408
	s_waitcnt lgkmcnt(5)
	v_mfma_f32_16x16x32_bf16 v[142:145], v[202:205], v[178:181], v[142:145]
	v_mfma_f32_16x16x32_bf16 v[138:141], v[202:205], v[182:185], v[138:141]
	v_mfma_f32_16x16x32_bf16 v[134:137], v[202:205], v[186:189], v[134:137]
	v_mfma_f32_16x16x32_bf16 v[130:133], v[202:205], v[190:193], v[130:133]
	ds_read_b128 v[202:205], v237 offset:6144
	ds_read_b128 v[246:249], v233 offset:18432
	s_waitcnt lgkmcnt(6)
	v_mfma_f32_16x16x32_bf16 v[126:129], v[206:209], v[178:181], v[126:129]
	v_mfma_f32_16x16x32_bf16 v[122:125], v[206:209], v[182:185], v[122:125]
	v_mfma_f32_16x16x32_bf16 v[118:121], v[206:209], v[186:189], v[118:121]
	v_mfma_f32_16x16x32_bf16 v[114:117], v[206:209], v[190:193], v[114:117]
	ds_read_b128 v[206:209], v237 offset:7168
	ds_read_b128 v[222:225], v233 offset:19456
	s_sub_i32 s35, s7, s1
	v_add_u32_e32 v236, s35, v236
	v_add_u32_e32 v237, s35, v237
	s_sub_i32 s35, s1, s7
	v_mad_i32_i24 v235, v221, s35, v220
	v_add_u32_e32 v235, s7, v235
	s_waitcnt lgkmcnt(1)
	s_barrier
	s_setprio 1
	v_mfma_f32_16x16x32_bf16 v[110:113], v[194:197], v[178:181], v[110:113]
	v_mfma_f32_16x16x32_bf16 v[106:109], v[194:197], v[182:185], v[106:109]
	v_mfma_f32_16x16x32_bf16 v[102:105], v[194:197], v[186:189], v[102:105]
	v_mfma_f32_16x16x32_bf16 v[98:101], v[194:197], v[190:193], v[98:101]
	ds_read_b128 v[194:197], v232
	s_waitcnt vmcnt(11)
	ds_write_b128 v235, v[2:5]
	v_mfma_f32_16x16x32_bf16 v[94:97], v[198:201], v[178:181], v[94:97]
	v_mfma_f32_16x16x32_bf16 v[90:93], v[198:201], v[182:185], v[90:93]
	v_mfma_f32_16x16x32_bf16 v[86:89], v[198:201], v[186:189], v[86:89]
	v_mfma_f32_16x16x32_bf16 v[82:85], v[198:201], v[190:193], v[82:85]
	ds_read_b128 v[198:201], v232 offset:1024
	s_waitcnt vmcnt(10)
	ds_write_b128 v235, v[6:9] offset:2048
	v_mfma_f32_16x16x32_bf16 v[78:81], v[202:205], v[178:181], v[78:81]
	v_mfma_f32_16x16x32_bf16 v[74:77], v[202:205], v[182:185], v[74:77]
	v_mfma_f32_16x16x32_bf16 v[70:73], v[202:205], v[186:189], v[70:73]
	v_mfma_f32_16x16x32_bf16 v[66:69], v[202:205], v[190:193], v[66:69]
	ds_read_b128 v[202:205], v232 offset:2048
	s_waitcnt vmcnt(9)
	ds_write_b128 v235, v[10:13] offset:4096
	v_mfma_f32_16x16x32_bf16 v[62:65], v[206:209], v[178:181], v[62:65]
	v_mfma_f32_16x16x32_bf16 v[58:61], v[206:209], v[182:185], v[58:61]
	v_mfma_f32_16x16x32_bf16 v[54:57], v[206:209], v[186:189], v[54:57]
	v_mfma_f32_16x16x32_bf16 v[50:53], v[206:209], v[190:193], v[50:53]
	ds_read_b128 v[206:209], v232 offset:3072
	s_waitcnt vmcnt(8)
	ds_write_b128 v235, v[14:17] offset:6144
	s_waitcnt lgkmcnt(7)
; template <int MODE>
; __device__ void gemm_tile2(const u16* __restrict__ X, int lda, const u16* __restrict__ W, int ldb, int K,
;                            int m0, int n0, u16* __restrict__ outb, int vbase,
;                            const float* resid, float* outf, unsigned char* smem) {
;     ...
;   G2_GLOAD(0, 0);
;   G2_GLOAD(1, 1);
;   __syncthreads();
;   G2_LSTORE(0, 0);
;   G2_GLOAD(0, 2);
;   __syncthreads();
;   for (int kt2 = 0; kt2 < nk; kt2 += 2) {
; #pragma unroll
;     for (int h = 0; h < 2; ++h) {
;       const int kt = kt2 + h;
;       const u16* st = sbase + h * G2STAGE;
;       bf16x8 fw[4], fx[4];
; #pragma unroll
;       for (int j = 0; j < 4; ++j) fw[j] = *(const bf16x8*)(st + 256 * G2S + (ww * 64 + j * 16 + l15) * G2S + fsw);
; #pragma unroll
;       for (int i = 0; i < 4; ++i) fx[i] = *(const bf16x8*)(st + (wx * 128 + i * 16 + l15) * G2S + fsw);
;       __builtin_amdgcn_sched_barrier(0);
;       __builtin_amdgcn_s_setprio(1);
; #pragma unroll
;       for (int i = 0; i < 4; ++i) {
; #pragma unroll
;         for (int j = 0; j < 4; ++j) {
;           if (MODE == 1) acc[i][j] = mfma16(fx[i], fw[j], acc[i][j]);
;           else acc[i][j] = mfma16(fw[j], fx[i], acc[i][j]);
;         }
;       }
;       __builtin_amdgcn_s_setprio(0);
;       __builtin_amdgcn_sched_barrier(0);
; #pragma unroll
;       for (int i = 0; i < 4; ++i) fx[i] = *(const bf16x8*)(st + (wx * 128 + (i + 4) * 16 + l15) * G2S + fsw);
;       __builtin_amdgcn_sched_barrier(0);
;       if (kt + 1 < nk) G2_LSTORE(1 - h, 1 - h);
;       if (kt + 3 < nk) G2_GLOAD(1 - h, kt + 3);
;       __builtin_amdgcn_sched_barrier(0);
;       __builtin_amdgcn_s_setprio(1);
; #pragma unroll
;       for (int i = 0; i < 4; ++i) {
; #pragma unroll
;         for (int j = 0; j < 4; ++j) {
;           if (MODE == 1) acc[i + 4][j] = mfma16(fx[i], fw[j], acc[i + 4][j]);
;           else acc[i + 4][j] = mfma16(fw[j], fx[i], acc[i + 4][j]);
;         }
;       }
;       __builtin_amdgcn_s_setprio(0);
;       __syncthreads();
;     }
;   }
	v_mfma_f32_16x16x32_bf16 v[174:177], v[194:197], v[238:241], v[174:177]
	v_mfma_f32_16x16x32_bf16 v[170:173], v[194:197], v[242:245], v[170:173]
	v_mfma_f32_16x16x32_bf16 v[166:169], v[194:197], v[246:249], v[166:169]
	v_mfma_f32_16x16x32_bf16 v[162:165], v[194:197], v[222:225], v[162:165]
	ds_read_b128 v[194:197], v232 offset:4096
	s_waitcnt vmcnt(7)
	ds_write_b128 v235, v[18:21] offset:8192
	s_waitcnt lgkmcnt(7)
	v_mfma_f32_16x16x32_bf16 v[158:161], v[198:201], v[238:241], v[158:161]
	v_mfma_f32_16x16x32_bf16 v[154:157], v[198:201], v[242:245], v[154:157]
	v_mfma_f32_16x16x32_bf16 v[150:153], v[198:201], v[246:249], v[150:153]
	v_mfma_f32_16x16x32_bf16 v[146:149], v[198:201], v[222:225], v[146:149]
	ds_read_b128 v[198:201], v232 offset:5120
	s_waitcnt vmcnt(6)
	ds_write_b128 v235, v[22:25] offset:10240
	s_waitcnt lgkmcnt(7)
	v_mfma_f32_16x16x32_bf16 v[142:145], v[202:205], v[238:241], v[142:145]
	v_mfma_f32_16x16x32_bf16 v[138:141], v[202:205], v[242:245], v[138:141]
	v_mfma_f32_16x16x32_bf16 v[134:137], v[202:205], v[246:249], v[134:137]
	v_mfma_f32_16x16x32_bf16 v[130:133], v[202:205], v[222:225], v[130:133]
	ds_read_b128 v[202:205], v232 offset:6144
	s_waitcnt vmcnt(5)
	ds_write_b128 v235, v[26:29] offset:12288
	s_waitcnt lgkmcnt(7)
	v_mfma_f32_16x16x32_bf16 v[126:129], v[206:209], v[238:241], v[126:129]
	v_mfma_f32_16x16x32_bf16 v[122:125], v[206:209], v[242:245], v[122:125]
	v_mfma_f32_16x16x32_bf16 v[118:121], v[206:209], v[246:249], v[118:121]
	v_mfma_f32_16x16x32_bf16 v[114:117], v[206:209], v[222:225], v[114:117]
	ds_read_b128 v[206:209], v232 offset:7168
	s_sub_i32 s35, s1, s6
	v_add_u32_e32 v233, s35, v233
	v_add_u32_e32 v232, s35, v232
	s_waitcnt vmcnt(4)
	ds_write_b128 v235, v[30:33] offset:14336
	s_waitcnt lgkmcnt(7)
	v_mfma_f32_16x16x32_bf16 v[110:113], v[194:197], v[238:241], v[110:113]
	v_mfma_f32_16x16x32_bf16 v[106:109], v[194:197], v[242:245], v[106:109]
	v_mfma_f32_16x16x32_bf16 v[102:105], v[194:197], v[246:249], v[102:105]
	v_mfma_f32_16x16x32_bf16 v[98:101], v[194:197], v[222:225], v[98:101]
	s_waitcnt vmcnt(3)
	ds_write_b128 v235, v[34:37] offset:16384
	s_waitcnt lgkmcnt(6)
	v_mfma_f32_16x16x32_bf16 v[94:97], v[198:201], v[238:241], v[94:97]
	v_mfma_f32_16x16x32_bf16 v[90:93], v[198:201], v[242:245], v[90:93]
	v_mfma_f32_16x16x32_bf16 v[86:89], v[198:201], v[246:249], v[86:89]
	v_mfma_f32_16x16x32_bf16 v[82:85], v[198:201], v[222:225], v[82:85]
	s_waitcnt vmcnt(2)
	ds_write_b128 v235, v[38:41] offset:18432
	s_waitcnt lgkmcnt(5)
	v_mfma_f32_16x16x32_bf16 v[78:81], v[202:205], v[238:241], v[78:81]
	v_mfma_f32_16x16x32_bf16 v[74:77], v[202:205], v[242:245], v[74:77]
	v_mfma_f32_16x16x32_bf16 v[70:73], v[202:205], v[246:249], v[70:73]
	v_mfma_f32_16x16x32_bf16 v[66:69], v[202:205], v[222:225], v[66:69]
	s_waitcnt vmcnt(1)
	ds_write_b128 v235, v[42:45] offset:20480
	s_waitcnt lgkmcnt(4)
	v_mfma_f32_16x16x32_bf16 v[62:65], v[206:209], v[238:241], v[62:65]
	v_mfma_f32_16x16x32_bf16 v[58:61], v[206:209], v[242:245], v[58:61]
	v_mfma_f32_16x16x32_bf16 v[54:57], v[206:209], v[246:249], v[54:57]
	v_mfma_f32_16x16x32_bf16 v[50:53], v[206:209], v[222:225], v[50:53]
	s_waitcnt vmcnt(0)
	ds_write_b128 v235, v[46:49] offset:22528
	s_waitcnt lgkmcnt(0)
	s_setprio 0
	s_barrier
	s_mov_b32 s35, s7
	s_mov_b32 s7, s6
	s_mov_b32 s6, s1
	s_mov_b32 s1, s35
	ds_read_b128 v[178:181], v236 offset:16384
	ds_read_b128 v[182:185], v236 offset:17408
	ds_read_b128 v[186:189], v236 offset:18432
	ds_read_b128 v[190:193], v236 offset:19456
	ds_read_b128 v[194:197], v237
	ds_read_b128 v[198:201], v237 offset:1024
	ds_read_b128 v[202:205], v237 offset:2048
	ds_read_b128 v[206:209], v237 offset:3072
	s_waitcnt lgkmcnt(3)
	v_mfma_f32_16x16x32_bf16 v[174:177], v[194:197], v[178:181], v[174:177]
	v_mfma_f32_16x16x32_bf16 v[170:173], v[194:197], v[182:185], v[170:173]
	v_mfma_f32_16x16x32_bf16 v[166:169], v[194:197], v[186:189], v[166:169]
	v_mfma_f32_16x16x32_bf16 v[162:165], v[194:197], v[190:193], v[162:165]
	ds_read_b128 v[194:197], v237 offset:4096
	ds_read_b128 v[238:241], v233 offset:16384
	s_waitcnt lgkmcnt(4)
	v_mfma_f32_16x16x32_bf16 v[158:161], v[198:201], v[178:181], v[158:161]
	v_mfma_f32_16x16x32_bf16 v[154:157], v[198:201], v[182:185], v[154:157]
	v_mfma_f32_16x16x32_bf16 v[150:153], v[198:201], v[186:189], v[150:153]
	v_mfma_f32_16x16x32_bf16 v[146:149], v[198:201], v[190:193], v[146:149]
	ds_read_b128 v[198:201], v237 offset:5120
	ds_read_b128 v[242:245], v233 offset:17408
	s_waitcnt lgkmcnt(5)
	v_mfma_f32_16x16x32_bf16 v[142:145], v[202:205], v[178:181], v[142:145]
	v_mfma_f32_16x16x32_bf16 v[138:141], v[202:205], v[182:185], v[138:141]
	v_mfma_f32_16x16x32_bf16 v[134:137], v[202:205], v[186:189], v[134:137]
	v_mfma_f32_16x16x32_bf16 v[130:133], v[202:205], v[190:193], v[130:133]
	ds_read_b128 v[202:205], v237 offset:6144
	ds_read_b128 v[246:249], v233 offset:18432
	s_waitcnt lgkmcnt(6)
	v_mfma_f32_16x16x32_bf16 v[126:129], v[206:209], v[178:181], v[126:129]
	v_mfma_f32_16x16x32_bf16 v[122:125], v[206:209], v[182:185], v[122:125]
	v_mfma_f32_16x16x32_bf16 v[118:121], v[206:209], v[186:189], v[118:121]
	v_mfma_f32_16x16x32_bf16 v[114:117], v[206:209], v[190:193], v[114:117]
	ds_read_b128 v[206:209], v237 offset:7168
	ds_read_b128 v[222:225], v233 offset:19456
	s_sub_i32 s35, s7, s1
	v_add_u32_e32 v236, s35, v236
	v_add_u32_e32 v237, s35, v237
	s_waitcnt lgkmcnt(1)
	s_barrier
; template <int MODE>
; __device__ void gemm_tile2(const u16* __restrict__ X, int lda, const u16* __restrict__ W, int ldb, int K,
;                            int m0, int n0, u16* __restrict__ outb, int vbase,
;                            const float* resid, float* outf, unsigned char* smem) {
;     ...
;   for (int kt2 = 0; kt2 < nk; kt2 += 2) {
; #pragma unroll
;     for (int h = 0; h < 2; ++h) {
;       const int kt = kt2 + h;
;       const u16* st = sbase + h * G2STAGE;
;       bf16x8 fw[4], fx[4];
; #pragma unroll
;       for (int j = 0; j < 4; ++j) fw[j] = *(const bf16x8*)(st + 256 * G2S + (ww * 64 + j * 16 + l15) * G2S + fsw);
; #pragma unroll
;       for (int i = 0; i < 4; ++i) fx[i] = *(const bf16x8*)(st + (wx * 128 + i * 16 + l15) * G2S + fsw);
;       __builtin_amdgcn_sched_barrier(0);
;       __builtin_amdgcn_s_setprio(1);
; #pragma unroll
;       for (int i = 0; i < 4; ++i) {
; #pragma unroll
;         for (int j = 0; j < 4; ++j) {
;           if (MODE == 1) acc[i][j] = mfma16(fx[i], fw[j], acc[i][j]);
;           else acc[i][j] = mfma16(fw[j], fx[i], acc[i][j]);
;         }
;       }
;       __builtin_amdgcn_s_setprio(0);
;       __builtin_amdgcn_sched_barrier(0);
; #pragma unroll
;       for (int i = 0; i < 4; ++i) fx[i] = *(const bf16x8*)(st + (wx * 128 + (i + 4) * 16 + l15) * G2S + fsw);
;       __builtin_amdgcn_sched_barrier(0);
;       if (kt + 1 < nk) G2_LSTORE(1 - h, 1 - h);
;       if (kt + 3 < nk) G2_GLOAD(1 - h, kt + 3);
;       __builtin_amdgcn_sched_barrier(0);
;       __builtin_amdgcn_s_setprio(1);
; #pragma unroll
;       for (int i = 0; i < 4; ++i) {
; #pragma unroll
;         for (int j = 0; j < 4; ++j) {
;           if (MODE == 1) acc[i + 4][j] = mfma16(fx[i], fw[j], acc[i + 4][j]);
;           else acc[i + 4][j] = mfma16(fw[j], fx[i], acc[i + 4][j]);
;         }
;       }
;       __builtin_amdgcn_s_setprio(0);
;       __syncthreads();
;     }
;   }
	s_setprio 1
	v_mfma_f32_16x16x32_bf16 v[110:113], v[194:197], v[178:181], v[110:113]
	v_mfma_f32_16x16x32_bf16 v[106:109], v[194:197], v[182:185], v[106:109]
	v_mfma_f32_16x16x32_bf16 v[102:105], v[194:197], v[186:189], v[102:105]
	v_mfma_f32_16x16x32_bf16 v[98:101], v[194:197], v[190:193], v[98:101]
	ds_read_b128 v[194:197], v232
	v_mfma_f32_16x16x32_bf16 v[94:97], v[198:201], v[178:181], v[94:97]
	v_mfma_f32_16x16x32_bf16 v[90:93], v[198:201], v[182:185], v[90:93]
	v_mfma_f32_16x16x32_bf16 v[86:89], v[198:201], v[186:189], v[86:89]
	v_mfma_f32_16x16x32_bf16 v[82:85], v[198:201], v[190:193], v[82:85]
	ds_read_b128 v[198:201], v232 offset:1024
	v_mfma_f32_16x16x32_bf16 v[78:81], v[202:205], v[178:181], v[78:81]
	v_mfma_f32_16x16x32_bf16 v[74:77], v[202:205], v[182:185], v[74:77]
	v_mfma_f32_16x16x32_bf16 v[70:73], v[202:205], v[186:189], v[70:73]
	v_mfma_f32_16x16x32_bf16 v[66:69], v[202:205], v[190:193], v[66:69]
	ds_read_b128 v[202:205], v232 offset:2048
	v_mfma_f32_16x16x32_bf16 v[62:65], v[206:209], v[178:181], v[62:65]
	v_mfma_f32_16x16x32_bf16 v[58:61], v[206:209], v[182:185], v[58:61]
	v_mfma_f32_16x16x32_bf16 v[54:57], v[206:209], v[186:189], v[54:57]
	v_mfma_f32_16x16x32_bf16 v[50:53], v[206:209], v[190:193], v[50:53]
	ds_read_b128 v[206:209], v232 offset:3072
	s_waitcnt lgkmcnt(3)
	v_mfma_f32_16x16x32_bf16 v[174:177], v[194:197], v[238:241], v[174:177]
	v_mfma_f32_16x16x32_bf16 v[170:173], v[194:197], v[242:245], v[170:173]
	v_mfma_f32_16x16x32_bf16 v[166:169], v[194:197], v[246:249], v[166:169]
	v_mfma_f32_16x16x32_bf16 v[162:165], v[194:197], v[222:225], v[162:165]
	ds_read_b128 v[194:197], v232 offset:4096
	s_waitcnt lgkmcnt(3)
	v_mfma_f32_16x16x32_bf16 v[158:161], v[198:201], v[238:241], v[158:161]
	v_mfma_f32_16x16x32_bf16 v[154:157], v[198:201], v[242:245], v[154:157]
	v_mfma_f32_16x16x32_bf16 v[150:153], v[198:201], v[246:249], v[150:153]
	v_mfma_f32_16x16x32_bf16 v[146:149], v[198:201], v[222:225], v[146:149]
	ds_read_b128 v[198:201], v232 offset:5120
	s_waitcnt lgkmcnt(3)
	v_mfma_f32_16x16x32_bf16 v[142:145], v[202:205], v[238:241], v[142:145]
	v_mfma_f32_16x16x32_bf16 v[138:141], v[202:205], v[242:245], v[138:141]
	v_mfma_f32_16x16x32_bf16 v[134:137], v[202:205], v[246:249], v[134:137]
	v_mfma_f32_16x16x32_bf16 v[130:133], v[202:205], v[222:225], v[130:133]
	ds_read_b128 v[202:205], v232 offset:6144
	s_waitcnt lgkmcnt(3)
	v_mfma_f32_16x16x32_bf16 v[126:129], v[206:209], v[238:241], v[126:129]
	v_mfma_f32_16x16x32_bf16 v[122:125], v[206:209], v[242:245], v[122:125]
	v_mfma_f32_16x16x32_bf16 v[118:121], v[206:209], v[246:249], v[118:121]
	v_mfma_f32_16x16x32_bf16 v[114:117], v[206:209], v[222:225], v[114:117]
	ds_read_b128 v[206:209], v232 offset:7168
	s_sub_i32 s35, s1, s6
	v_add_u32_e32 v233, s35, v233
	v_add_u32_e32 v232, s35, v232
	s_waitcnt lgkmcnt(3)
	v_mfma_f32_16x16x32_bf16 v[110:113], v[194:197], v[238:241], v[110:113]
	v_mfma_f32_16x16x32_bf16 v[106:109], v[194:197], v[242:245], v[106:109]
	v_mfma_f32_16x16x32_bf16 v[102:105], v[194:197], v[246:249], v[102:105]
	v_mfma_f32_16x16x32_bf16 v[98:101], v[194:197], v[222:225], v[98:101]
	s_waitcnt lgkmcnt(2)
	v_mfma_f32_16x16x32_bf16 v[94:97], v[198:201], v[238:241], v[94:97]
	v_mfma_f32_16x16x32_bf16 v[90:93], v[198:201], v[242:245], v[90:93]
	v_mfma_f32_16x16x32_bf16 v[86:89], v[198:201], v[246:249], v[86:89]
	v_mfma_f32_16x16x32_bf16 v[82:85], v[198:201], v[222:225], v[82:85]
	s_waitcnt lgkmcnt(1)
	v_mfma_f32_16x16x32_bf16 v[78:81], v[202:205], v[238:241], v[78:81]
	v_mfma_f32_16x16x32_bf16 v[74:77], v[202:205], v[242:245], v[74:77]
	v_mfma_f32_16x16x32_bf16 v[70:73], v[202:205], v[246:249], v[70:73]
	v_mfma_f32_16x16x32_bf16 v[66:69], v[202:205], v[222:225], v[66:69]
	s_waitcnt lgkmcnt(0)
	v_mfma_f32_16x16x32_bf16 v[62:65], v[206:209], v[238:241], v[62:65]
	v_mfma_f32_16x16x32_bf16 v[58:61], v[206:209], v[242:245], v[58:61]
	v_mfma_f32_16x16x32_bf16 v[54:57], v[206:209], v[246:249], v[54:57]
	v_mfma_f32_16x16x32_bf16 v[50:53], v[206:209], v[222:225], v[50:53]
	s_setprio 0
	s_barrier
	s_mov_b32 s35, s7
	s_mov_b32 s7, s6
	s_mov_b32 s6, s1
	s_mov_b32 s1, s35
	s_nop 7
	v_and_b32_e32 v232, 15, v0
	s_branch .LBB0_285

; template <int MODE>
; __device__ void gemm_tile2(const u16* __restrict__ X, int lda, const u16* __restrict__ W, int ldb, int K,
;                            int m0, int n0, u16* __restrict__ outb, int vbase,
;                            const float* resid, float* outf, unsigned char* smem) {
;     ...
;   G2_GLOAD(0, 0);
;   G2_GLOAD(1, 1);
;   __syncthreads();
;   G2_LSTORE(0, 0);
;   G2_GLOAD(0, 2);
;   __syncthreads();
;   for (int kt2 = 0; kt2 < nk; kt2 += 2) {
; #pragma unroll
;     for (int h = 0; h < 2; ++h) {
;       const int kt = kt2 + h;
;       const u16* st = sbase + h * G2STAGE;
;       bf16x8 fw[4], fx[4];
; #pragma unroll
;       for (int j = 0; j < 4; ++j) fw[j] = *(const bf16x8*)(st + 256 * G2S + (ww * 64 + j * 16 + l15) * G2S + fsw);
; #pragma unroll
;       for (int i = 0; i < 4; ++i) fx[i] = *(const bf16x8*)(st + (wx * 128 + i * 16 + l15) * G2S + fsw);
;       __builtin_amdgcn_sched_barrier(0);
;       __builtin_amdgcn_s_setprio(1);
; #pragma unroll
;       for (int i = 0; i < 4; ++i) {
; #pragma unroll
;         for (int j = 0; j < 4; ++j) {
;           if (MODE == 1) acc[i][j] = mfma16(fx[i], fw[j], acc[i][j]);
;           else acc[i][j] = mfma16(fw[j], fx[i], acc[i][j]);
;         }
;       }
;       __builtin_amdgcn_s_setprio(0);
;       __builtin_amdgcn_sched_barrier(0);
; #pragma unroll
;       for (int i = 0; i < 4; ++i) fx[i] = *(const bf16x8*)(st + (wx * 128 + (i + 4) * 16 + l15) * G2S + fsw);
;       __builtin_amdgcn_sched_barrier(0);
;       if (kt + 1 < nk) G2_LSTORE(1 - h, 1 - h);
;       if (kt + 3 < nk) G2_GLOAD(1 - h, kt + 3);
;       __builtin_amdgcn_sched_barrier(0);
;       __builtin_amdgcn_s_setprio(1);
; #pragma unroll
;       for (int i = 0; i < 4; ++i) {
; #pragma unroll
;         for (int j = 0; j < 4; ++j) {
;           if (MODE == 1) acc[i + 4][j] = mfma16(fx[i], fw[j], acc[i + 4][j]);
;           else acc[i + 4][j] = mfma16(fw[j], fx[i], acc[i + 4][j]);
;         }
;       }
;       __builtin_amdgcn_s_setprio(0);
;       __syncthreads();
;     }
;   }
.Lf2_loop:
	s_waitcnt lgkmcnt(3)
	v_mfma_f32_16x16x32_bf16 v[126:129], v[178:181], v[194:197], v[126:129]
	v_mfma_f32_16x16x32_bf16 v[122:125], v[182:185], v[194:197], v[122:125]
	v_mfma_f32_16x16x32_bf16 v[118:121], v[186:189], v[194:197], v[118:121]
	v_mfma_f32_16x16x32_bf16 v[114:117], v[190:193], v[194:197], v[114:117]
	ds_read_b128 v[194:197], v236 offset:4096
	ds_read_b128 v[238:241], v232 offset:16384
	s_waitcnt lgkmcnt(4)
	v_mfma_f32_16x16x32_bf16 v[110:113], v[178:181], v[198:201], v[110:113]
	v_mfma_f32_16x16x32_bf16 v[106:109], v[182:185], v[198:201], v[106:109]
	v_mfma_f32_16x16x32_bf16 v[102:105], v[186:189], v[198:201], v[102:105]
	v_mfma_f32_16x16x32_bf16 v[98:101], v[190:193], v[198:201], v[98:101]
	ds_read_b128 v[198:201], v236 offset:5120
	ds_read_b128 v[242:245], v232 offset:17408
	s_waitcnt lgkmcnt(5)
	v_mfma_f32_16x16x32_bf16 v[94:97], v[178:181], v[202:205], v[94:97]
	v_mfma_f32_16x16x32_bf16 v[90:93], v[182:185], v[202:205], v[90:93]
	v_mfma_f32_16x16x32_bf16 v[86:89], v[186:189], v[202:205], v[86:89]
	v_mfma_f32_16x16x32_bf16 v[82:85], v[190:193], v[202:205], v[82:85]
	ds_read_b128 v[202:205], v236 offset:6144
	ds_read_b128 v[246:249], v232 offset:18432
	s_waitcnt lgkmcnt(6)
	v_mfma_f32_16x16x32_bf16 v[78:81], v[178:181], v[206:209], v[78:81]
	v_mfma_f32_16x16x32_bf16 v[74:77], v[182:185], v[206:209], v[74:77]
	v_mfma_f32_16x16x32_bf16 v[70:73], v[186:189], v[206:209], v[70:73]
	v_mfma_f32_16x16x32_bf16 v[66:69], v[190:193], v[206:209], v[66:69]
	ds_read_b128 v[206:209], v236 offset:7168
	ds_read_b128 v[222:225], v232 offset:19456
	s_sub_i32 s35, s31, s7
	v_add_u32_e32 v235, s35, v235
	v_add_u32_e32 v236, s35, v236
	s_sub_i32 s35, s7, s31
	v_mad_i32_i24 v234, v221, s35, v220
	v_add_u32_e32 v234, s31, v234
	s_waitcnt lgkmcnt(1)
	s_barrier
	s_setprio 1
	v_mfma_f32_16x16x32_bf16 v[62:65], v[178:181], v[194:197], v[62:65]
	v_mfma_f32_16x16x32_bf16 v[58:61], v[182:185], v[194:197], v[58:61]
	v_mfma_f32_16x16x32_bf16 v[54:57], v[186:189], v[194:197], v[54:57]
	v_mfma_f32_16x16x32_bf16 v[50:53], v[190:193], v[194:197], v[50:53]
	ds_read_b128 v[194:197], v237
	s_waitcnt vmcnt(11)
	ds_write_b128 v234, v[130:133]
	buffer_load_dwordx4 v[130:133], v218, s[24:27], 0 offen
	v_mfma_f32_16x16x32_bf16 v[46:49], v[178:181], v[198:201], v[46:49]
	v_mfma_f32_16x16x32_bf16 v[42:45], v[182:185], v[198:201], v[42:45]
	v_mfma_f32_16x16x32_bf16 v[38:41], v[186:189], v[198:201], v[38:41]
	v_mfma_f32_16x16x32_bf16 v[34:37], v[190:193], v[198:201], v[34:37]
	ds_read_b128 v[198:201], v237 offset:1024
	s_waitcnt vmcnt(11)
	ds_write_b128 v234, v[134:137] offset:2048
	buffer_load_dwordx4 v[134:137], v219, s[24:27], 0 offen
	v_mfma_f32_16x16x32_bf16 v[30:33], v[178:181], v[202:205], v[30:33]
	v_mfma_f32_16x16x32_bf16 v[26:29], v[182:185], v[202:205], v[26:29]
	v_mfma_f32_16x16x32_bf16 v[22:25], v[186:189], v[202:205], v[22:25]
	v_mfma_f32_16x16x32_bf16 v[18:21], v[190:193], v[202:205], v[18:21]
	ds_read_b128 v[202:205], v237 offset:2048
	s_waitcnt vmcnt(11)
	ds_write_b128 v234, v[138:141] offset:4096
	buffer_load_dwordx4 v[138:141], v218, s[24:27], s27 offen
	v_mfma_f32_16x16x32_bf16 v[14:17], v[178:181], v[206:209], v[14:17]
	v_mfma_f32_16x16x32_bf16 v[10:13], v[182:185], v[206:209], v[10:13]
	v_mfma_f32_16x16x32_bf16 v[6:9], v[186:189], v[206:209], v[6:9]
	v_mfma_f32_16x16x32_bf16 v[2:5], v[190:193], v[206:209], v[2:5]
	ds_read_b128 v[206:209], v237 offset:3072
	s_waitcnt vmcnt(11)
	ds_write_b128 v234, v[142:145] offset:6144
	buffer_load_dwordx4 v[142:145], v219, s[24:27], s27 offen
	s_waitcnt lgkmcnt(7)
	v_mfma_f32_16x16x32_bf16 v[126:129], v[238:241], v[194:197], v[126:129]
	v_mfma_f32_16x16x32_bf16 v[122:125], v[242:245], v[194:197], v[122:125]
	v_mfma_f32_16x16x32_bf16 v[118:121], v[246:249], v[194:197], v[118:121]
	v_mfma_f32_16x16x32_bf16 v[114:117], v[222:225], v[194:197], v[114:117]
	ds_read_b128 v[194:197], v237 offset:4096
	s_waitcnt vmcnt(11)
	ds_write_b128 v234, v[146:149] offset:8192
	buffer_load_dwordx4 v[146:149], v218, s[24:27], s77 offen
	s_waitcnt lgkmcnt(7)
	v_mfma_f32_16x16x32_bf16 v[110:113], v[238:241], v[198:201], v[110:113]
	v_mfma_f32_16x16x32_bf16 v[106:109], v[242:245], v[198:201], v[106:109]
	v_mfma_f32_16x16x32_bf16 v[102:105], v[246:249], v[198:201], v[102:105]
	v_mfma_f32_16x16x32_bf16 v[98:101], v[222:225], v[198:201], v[98:101]
	ds_read_b128 v[198:201], v237 offset:5120
	s_waitcnt vmcnt(11)
	ds_write_b128 v234, v[150:153] offset:10240
	buffer_load_dwordx4 v[150:153], v219, s[24:27], s77 offen
	s_waitcnt lgkmcnt(7)
	v_mfma_f32_16x16x32_bf16 v[94:97], v[238:241], v[202:205], v[94:97]
	v_mfma_f32_16x16x32_bf16 v[90:93], v[242:245], v[202:205], v[90:93]
	v_mfma_f32_16x16x32_bf16 v[86:89], v[246:249], v[202:205], v[86:89]
	v_mfma_f32_16x16x32_bf16 v[82:85], v[222:225], v[202:205], v[82:85]
	ds_read_b128 v[202:205], v237 offset:6144
	s_waitcnt vmcnt(11)
	ds_write_b128 v234, v[154:157] offset:12288
	buffer_load_dwordx4 v[154:157], v218, s[24:27], s78 offen
	s_waitcnt lgkmcnt(7)
	v_mfma_f32_16x16x32_bf16 v[78:81], v[238:241], v[206:209], v[78:81]
	v_mfma_f32_16x16x32_bf16 v[74:77], v[242:245], v[206:209], v[74:77]
	v_mfma_f32_16x16x32_bf16 v[70:73], v[246:249], v[206:209], v[70:73]
	v_mfma_f32_16x16x32_bf16 v[66:69], v[222:225], v[206:209], v[66:69]
	ds_read_b128 v[206:209], v237 offset:7168
	s_sub_i32 s35, s7, s30
	v_add_u32_e32 v232, s35, v232
	v_add_u32_e32 v237, s35, v237
	s_waitcnt vmcnt(11)
	ds_write_b128 v234, v[158:161] offset:14336
	buffer_load_dwordx4 v[158:161], v219, s[24:27], s78 offen
	s_waitcnt lgkmcnt(7)
; template <int MODE>
; __device__ void gemm_tile2(const u16* __restrict__ X, int lda, const u16* __restrict__ W, int ldb, int K,
;                            int m0, int n0, u16* __restrict__ outb, int vbase,
;                            const float* resid, float* outf, unsigned char* smem) {
;     ...
;   G2_GLOAD(0, 0);
;   G2_GLOAD(1, 1);
;   __syncthreads();
;   G2_LSTORE(0, 0);
;   G2_GLOAD(0, 2);
;   __syncthreads();
;   for (int kt2 = 0; kt2 < nk; kt2 += 2) {
; #pragma unroll
;     for (int h = 0; h < 2; ++h) {
;       const int kt = kt2 + h;
;       const u16* st = sbase + h * G2STAGE;
;       bf16x8 fw[4], fx[4];
; #pragma unroll
;       for (int j = 0; j < 4; ++j) fw[j] = *(const bf16x8*)(st + 256 * G2S + (ww * 64 + j * 16 + l15) * G2S + fsw);
; #pragma unroll
;       for (int i = 0; i < 4; ++i) fx[i] = *(const bf16x8*)(st + (wx * 128 + i * 16 + l15) * G2S + fsw);
;       __builtin_amdgcn_sched_barrier(0);
;       __builtin_amdgcn_s_setprio(1);
; #pragma unroll
;       for (int i = 0; i < 4; ++i) {
; #pragma unroll
;         for (int j = 0; j < 4; ++j) {
;           if (MODE == 1) acc[i][j] = mfma16(fx[i], fw[j], acc[i][j]);
;           else acc[i][j] = mfma16(fw[j], fx[i], acc[i][j]);
;         }
;       }
;       __builtin_amdgcn_s_setprio(0);
;       __builtin_amdgcn_sched_barrier(0);
; #pragma unroll
;       for (int i = 0; i < 4; ++i) fx[i] = *(const bf16x8*)(st + (wx * 128 + (i + 4) * 16 + l15) * G2S + fsw);
;       __builtin_amdgcn_sched_barrier(0);
;       if (kt + 1 < nk) G2_LSTORE(1 - h, 1 - h);
;       if (kt + 3 < nk) G2_GLOAD(1 - h, kt + 3);
;       __builtin_amdgcn_sched_barrier(0);
;       __builtin_amdgcn_s_setprio(1);
; #pragma unroll
;       for (int i = 0; i < 4; ++i) {
; #pragma unroll
;         for (int j = 0; j < 4; ++j) {
;           if (MODE == 1) acc[i + 4][j] = mfma16(fx[i], fw[j], acc[i + 4][j]);
;           else acc[i + 4][j] = mfma16(fw[j], fx[i], acc[i + 4][j]);
;         }
;       }
;       __builtin_amdgcn_s_setprio(0);
;       __syncthreads();
;     }
;   }
	v_mfma_f32_16x16x32_bf16 v[62:65], v[238:241], v[194:197], v[62:65]
	v_mfma_f32_16x16x32_bf16 v[58:61], v[242:245], v[194:197], v[58:61]
	v_mfma_f32_16x16x32_bf16 v[54:57], v[246:249], v[194:197], v[54:57]
	v_mfma_f32_16x16x32_bf16 v[50:53], v[222:225], v[194:197], v[50:53]
	s_waitcnt vmcnt(11)
	ds_write_b128 v234, v[162:165] offset:16384
	buffer_load_dwordx4 v[162:165], v218, s[40:43], 0 offen
	s_waitcnt lgkmcnt(6)
	v_mfma_f32_16x16x32_bf16 v[46:49], v[238:241], v[198:201], v[46:49]
	v_mfma_f32_16x16x32_bf16 v[42:45], v[242:245], v[198:201], v[42:45]
	v_mfma_f32_16x16x32_bf16 v[38:41], v[246:249], v[198:201], v[38:41]
	v_mfma_f32_16x16x32_bf16 v[34:37], v[222:225], v[198:201], v[34:37]
	s_waitcnt vmcnt(11)
	ds_write_b128 v234, v[166:169] offset:18432
	buffer_load_dwordx4 v[166:169], v219, s[40:43], 0 offen
	s_waitcnt lgkmcnt(5)
	v_mfma_f32_16x16x32_bf16 v[30:33], v[238:241], v[202:205], v[30:33]
	v_mfma_f32_16x16x32_bf16 v[26:29], v[242:245], v[202:205], v[26:29]
	v_mfma_f32_16x16x32_bf16 v[22:25], v[246:249], v[202:205], v[22:25]
	v_mfma_f32_16x16x32_bf16 v[18:21], v[222:225], v[202:205], v[18:21]
	s_waitcnt vmcnt(11)
	ds_write_b128 v234, v[170:173] offset:20480
	buffer_load_dwordx4 v[170:173], v218, s[40:43], s27 offen
	s_waitcnt lgkmcnt(4)
	v_mfma_f32_16x16x32_bf16 v[14:17], v[238:241], v[206:209], v[14:17]
	v_mfma_f32_16x16x32_bf16 v[10:13], v[242:245], v[206:209], v[10:13]
	v_mfma_f32_16x16x32_bf16 v[6:9], v[246:249], v[206:209], v[6:9]
	v_mfma_f32_16x16x32_bf16 v[2:5], v[222:225], v[206:209], v[2:5]
	s_waitcnt vmcnt(11)
	ds_write_b128 v234, v[174:177] offset:22528
	buffer_load_dwordx4 v[174:177], v219, s[40:43], s27 offen
	v_add_u32_e32 v218, 0x80, v218
	v_add_u32_e32 v219, 0x80, v219
	s_waitcnt lgkmcnt(0)
	s_setprio 0
	s_barrier
	s_mov_b32 s35, s31
	s_mov_b32 s31, s30
	s_mov_b32 s30, s7
	s_mov_b32 s7, s35
	ds_read_b128 v[178:181], v235 offset:16384
	ds_read_b128 v[182:185], v235 offset:17408
	ds_read_b128 v[186:189], v235 offset:18432
	ds_read_b128 v[190:193], v235 offset:19456
	ds_read_b128 v[194:197], v236
	ds_read_b128 v[198:201], v236 offset:1024
	ds_read_b128 v[202:205], v236 offset:2048
	ds_read_b128 v[206:209], v236 offset:3072
	s_add_u32 s6, s6, 1
	s_cmp_lt_u32 s6, 14
	s_cbranch_scc1 .Lf2_loop
	s_waitcnt lgkmcnt(3)
	v_mfma_f32_16x16x32_bf16 v[126:129], v[178:181], v[194:197], v[126:129]
	v_mfma_f32_16x16x32_bf16 v[122:125], v[182:185], v[194:197], v[122:125]
	v_mfma_f32_16x16x32_bf16 v[118:121], v[186:189], v[194:197], v[118:121]
	v_mfma_f32_16x16x32_bf16 v[114:117], v[190:193], v[194:197], v[114:117]
	ds_read_b128 v[194:197], v236 offset:4096
	ds_read_b128 v[238:241], v232 offset:16384
	s_waitcnt lgkmcnt(4)
	v_mfma_f32_16x16x32_bf16 v[110:113], v[178:181], v[198:201], v[110:113]
	v_mfma_f32_16x16x32_bf16 v[106:109], v[182:185], v[198:201], v[106:109]
	v_mfma_f32_16x16x32_bf16 v[102:105], v[186:189], v[198:201], v[102:105]
	v_mfma_f32_16x16x32_bf16 v[98:101], v[190:193], v[198:201], v[98:101]
	ds_read_b128 v[198:201], v236 offset:5120
	ds_read_b128 v[242:245], v232 offset:17408
	s_waitcnt lgkmcnt(5)
	v_mfma_f32_16x16x32_bf16 v[94:97], v[178:181], v[202:205], v[94:97]
	v_mfma_f32_16x16x32_bf16 v[90:93], v[182:185], v[202:205], v[90:93]
	v_mfma_f32_16x16x32_bf16 v[86:89], v[186:189], v[202:205], v[86:89]
	v_mfma_f32_16x16x32_bf16 v[82:85], v[190:193], v[202:205], v[82:85]
	ds_read_b128 v[202:205], v236 offset:6144
	ds_read_b128 v[246:249], v232 offset:18432
	s_waitcnt lgkmcnt(6)
	v_mfma_f32_16x16x32_bf16 v[78:81], v[178:181], v[206:209], v[78:81]
	v_mfma_f32_16x16x32_bf16 v[74:77], v[182:185], v[206:209], v[74:77]
	v_mfma_f32_16x16x32_bf16 v[70:73], v[186:189], v[206:209], v[70:73]
	v_mfma_f32_16x16x32_bf16 v[66:69], v[190:193], v[206:209], v[66:69]
	ds_read_b128 v[206:209], v236 offset:7168
	ds_read_b128 v[222:225], v232 offset:19456
	s_sub_i32 s35, s31, s7
	v_add_u32_e32 v235, s35, v235
	v_add_u32_e32 v236, s35, v236
	s_sub_i32 s35, s7, s31
	v_mad_i32_i24 v234, v221, s35, v220
	v_add_u32_e32 v234, s31, v234
	s_waitcnt lgkmcnt(1)
	s_barrier
	s_setprio 1
	v_mfma_f32_16x16x32_bf16 v[62:65], v[178:181], v[194:197], v[62:65]
	v_mfma_f32_16x16x32_bf16 v[58:61], v[182:185], v[194:197], v[58:61]
	v_mfma_f32_16x16x32_bf16 v[54:57], v[186:189], v[194:197], v[54:57]
	v_mfma_f32_16x16x32_bf16 v[50:53], v[190:193], v[194:197], v[50:53]
	ds_read_b128 v[194:197], v237
	s_waitcnt vmcnt(11)
	ds_write_b128 v234, v[130:133]
	v_mfma_f32_16x16x32_bf16 v[46:49], v[178:181], v[198:201], v[46:49]
	v_mfma_f32_16x16x32_bf16 v[42:45], v[182:185], v[198:201], v[42:45]
	v_mfma_f32_16x16x32_bf16 v[38:41], v[186:189], v[198:201], v[38:41]
	v_mfma_f32_16x16x32_bf16 v[34:37], v[190:193], v[198:201], v[34:37]
	ds_read_b128 v[198:201], v237 offset:1024
	s_waitcnt vmcnt(10)
	ds_write_b128 v234, v[134:137] offset:2048
	v_mfma_f32_16x16x32_bf16 v[30:33], v[178:181], v[202:205], v[30:33]
	v_mfma_f32_16x16x32_bf16 v[26:29], v[182:185], v[202:205], v[26:29]
	v_mfma_f32_16x16x32_bf16 v[22:25], v[186:189], v[202:205], v[22:25]
	v_mfma_f32_16x16x32_bf16 v[18:21], v[190:193], v[202:205], v[18:21]
	ds_read_b128 v[202:205], v237 offset:2048
	s_waitcnt vmcnt(9)
	ds_write_b128 v234, v[138:141] offset:4096
	v_mfma_f32_16x16x32_bf16 v[14:17], v[178:181], v[206:209], v[14:17]
	v_mfma_f32_16x16x32_bf16 v[10:13], v[182:185], v[206:209], v[10:13]
	v_mfma_f32_16x16x32_bf16 v[6:9], v[186:189], v[206:209], v[6:9]
	v_mfma_f32_16x16x32_bf16 v[2:5], v[190:193], v[206:209], v[2:5]
	ds_read_b128 v[206:209], v237 offset:3072
	s_waitcnt vmcnt(8)
	ds_write_b128 v234, v[142:145] offset:6144
	s_waitcnt lgkmcnt(7)
; template <int MODE>
; __device__ void gemm_tile2(const u16* __restrict__ X, int lda, const u16* __restrict__ W, int ldb, int K,
;                            int m0, int n0, u16* __restrict__ outb, int vbase,
;                            const float* resid, float* outf, unsigned char* smem) {
;     ...
;   G2_GLOAD(0, 0);
;   G2_GLOAD(1, 1);
;   __syncthreads();
;   G2_LSTORE(0, 0);
;   G2_GLOAD(0, 2);
;   __syncthreads();
;   for (int kt2 = 0; kt2 < nk; kt2 += 2) {
; #pragma unroll
;     for (int h = 0; h < 2; ++h) {
;       const int kt = kt2 + h;
;       const u16* st = sbase + h * G2STAGE;
;       bf16x8 fw[4], fx[4];
; #pragma unroll
;       for (int j = 0; j < 4; ++j) fw[j] = *(const bf16x8*)(st + 256 * G2S + (ww * 64 + j * 16 + l15) * G2S + fsw);
; #pragma unroll
;       for (int i = 0; i < 4; ++i) fx[i] = *(const bf16x8*)(st + (wx * 128 + i * 16 + l15) * G2S + fsw);
;       __builtin_amdgcn_sched_barrier(0);
;       __builtin_amdgcn_s_setprio(1);
; #pragma unroll
;       for (int i = 0; i < 4; ++i) {
; #pragma unroll
;         for (int j = 0; j < 4; ++j) {
;           if (MODE == 1) acc[i][j] = mfma16(fx[i], fw[j], acc[i][j]);
;           else acc[i][j] = mfma16(fw[j], fx[i], acc[i][j]);
;         }
;       }
;       __builtin_amdgcn_s_setprio(0);
;       __builtin_amdgcn_sched_barrier(0);
; #pragma unroll
;       for (int i = 0; i < 4; ++i) fx[i] = *(const bf16x8*)(st + (wx * 128 + (i + 4) * 16 + l15) * G2S + fsw);
;       __builtin_amdgcn_sched_barrier(0);
;       if (kt + 1 < nk) G2_LSTORE(1 - h, 1 - h);
;       if (kt + 3 < nk) G2_GLOAD(1 - h, kt + 3);
;       __builtin_amdgcn_sched_barrier(0);
;       __builtin_amdgcn_s_setprio(1);
; #pragma unroll
;       for (int i = 0; i < 4; ++i) {
; #pragma unroll
;         for (int j = 0; j < 4; ++j) {
;           if (MODE == 1) acc[i + 4][j] = mfma16(fx[i], fw[j], acc[i + 4][j]);
;           else acc[i + 4][j] = mfma16(fw[j], fx[i], acc[i + 4][j]);
;         }
;       }
;       __builtin_amdgcn_s_setprio(0);
;       __syncthreads();
;     }
;   }
	v_mfma_f32_16x16x32_bf16 v[126:129], v[238:241], v[194:197], v[126:129]
	v_mfma_f32_16x16x32_bf16 v[122:125], v[242:245], v[194:197], v[122:125]
	v_mfma_f32_16x16x32_bf16 v[118:121], v[246:249], v[194:197], v[118:121]
	v_mfma_f32_16x16x32_bf16 v[114:117], v[222:225], v[194:197], v[114:117]
	ds_read_b128 v[194:197], v237 offset:4096
	s_waitcnt vmcnt(7)
	ds_write_b128 v234, v[146:149] offset:8192
	s_waitcnt lgkmcnt(7)
	v_mfma_f32_16x16x32_bf16 v[110:113], v[238:241], v[198:201], v[110:113]
	v_mfma_f32_16x16x32_bf16 v[106:109], v[242:245], v[198:201], v[106:109]
	v_mfma_f32_16x16x32_bf16 v[102:105], v[246:249], v[198:201], v[102:105]
	v_mfma_f32_16x16x32_bf16 v[98:101], v[222:225], v[198:201], v[98:101]
	ds_read_b128 v[198:201], v237 offset:5120
	s_waitcnt vmcnt(6)
	ds_write_b128 v234, v[150:153] offset:10240
	s_waitcnt lgkmcnt(7)
	v_mfma_f32_16x16x32_bf16 v[94:97], v[238:241], v[202:205], v[94:97]
	v_mfma_f32_16x16x32_bf16 v[90:93], v[242:245], v[202:205], v[90:93]
	v_mfma_f32_16x16x32_bf16 v[86:89], v[246:249], v[202:205], v[86:89]
	v_mfma_f32_16x16x32_bf16 v[82:85], v[222:225], v[202:205], v[82:85]
	ds_read_b128 v[202:205], v237 offset:6144
	s_waitcnt vmcnt(5)
	ds_write_b128 v234, v[154:157] offset:12288
	s_waitcnt lgkmcnt(7)
	v_mfma_f32_16x16x32_bf16 v[78:81], v[238:241], v[206:209], v[78:81]
	v_mfma_f32_16x16x32_bf16 v[74:77], v[242:245], v[206:209], v[74:77]
	v_mfma_f32_16x16x32_bf16 v[70:73], v[246:249], v[206:209], v[70:73]
	v_mfma_f32_16x16x32_bf16 v[66:69], v[222:225], v[206:209], v[66:69]
	ds_read_b128 v[206:209], v237 offset:7168
	s_sub_i32 s35, s7, s30
	v_add_u32_e32 v232, s35, v232
	v_add_u32_e32 v237, s35, v237
	s_waitcnt vmcnt(4)
	ds_write_b128 v234, v[158:161] offset:14336
	s_waitcnt lgkmcnt(7)
	v_mfma_f32_16x16x32_bf16 v[62:65], v[238:241], v[194:197], v[62:65]
	v_mfma_f32_16x16x32_bf16 v[58:61], v[242:245], v[194:197], v[58:61]
	v_mfma_f32_16x16x32_bf16 v[54:57], v[246:249], v[194:197], v[54:57]
	v_mfma_f32_16x16x32_bf16 v[50:53], v[222:225], v[194:197], v[50:53]
	s_waitcnt vmcnt(3)
	ds_write_b128 v234, v[162:165] offset:16384
	s_waitcnt lgkmcnt(6)
	v_mfma_f32_16x16x32_bf16 v[46:49], v[238:241], v[198:201], v[46:49]
	v_mfma_f32_16x16x32_bf16 v[42:45], v[242:245], v[198:201], v[42:45]
	v_mfma_f32_16x16x32_bf16 v[38:41], v[246:249], v[198:201], v[38:41]
	v_mfma_f32_16x16x32_bf16 v[34:37], v[222:225], v[198:201], v[34:37]
	s_waitcnt vmcnt(2)
	ds_write_b128 v234, v[166:169] offset:18432
	s_waitcnt lgkmcnt(5)
	v_mfma_f32_16x16x32_bf16 v[30:33], v[238:241], v[202:205], v[30:33]
	v_mfma_f32_16x16x32_bf16 v[26:29], v[242:245], v[202:205], v[26:29]
	v_mfma_f32_16x16x32_bf16 v[22:25], v[246:249], v[202:205], v[22:25]
	v_mfma_f32_16x16x32_bf16 v[18:21], v[222:225], v[202:205], v[18:21]
	s_waitcnt vmcnt(1)
	ds_write_b128 v234, v[170:173] offset:20480
	s_waitcnt lgkmcnt(4)
	v_mfma_f32_16x16x32_bf16 v[14:17], v[238:241], v[206:209], v[14:17]
	v_mfma_f32_16x16x32_bf16 v[10:13], v[242:245], v[206:209], v[10:13]
	v_mfma_f32_16x16x32_bf16 v[6:9], v[246:249], v[206:209], v[6:9]
	v_mfma_f32_16x16x32_bf16 v[2:5], v[222:225], v[206:209], v[2:5]
	s_waitcnt vmcnt(0)
	ds_write_b128 v234, v[174:177] offset:22528
	s_waitcnt lgkmcnt(0)
	s_setprio 0
	s_barrier
	s_mov_b32 s35, s31
	s_mov_b32 s31, s30
	s_mov_b32 s30, s7
	s_mov_b32 s7, s35
	ds_read_b128 v[178:181], v235 offset:16384
	ds_read_b128 v[182:185], v235 offset:17408
	ds_read_b128 v[186:189], v235 offset:18432
	ds_read_b128 v[190:193], v235 offset:19456
	ds_read_b128 v[194:197], v236
	ds_read_b128 v[198:201], v236 offset:1024
	ds_read_b128 v[202:205], v236 offset:2048
	ds_read_b128 v[206:209], v236 offset:3072
	s_waitcnt lgkmcnt(3)
	v_mfma_f32_16x16x32_bf16 v[126:129], v[178:181], v[194:197], v[126:129]
	v_mfma_f32_16x16x32_bf16 v[122:125], v[182:185], v[194:197], v[122:125]
	v_mfma_f32_16x16x32_bf16 v[118:121], v[186:189], v[194:197], v[118:121]
	v_mfma_f32_16x16x32_bf16 v[114:117], v[190:193], v[194:197], v[114:117]
	ds_read_b128 v[194:197], v236 offset:4096
	ds_read_b128 v[238:241], v232 offset:16384
	s_waitcnt lgkmcnt(4)
	v_mfma_f32_16x16x32_bf16 v[110:113], v[178:181], v[198:201], v[110:113]
	v_mfma_f32_16x16x32_bf16 v[106:109], v[182:185], v[198:201], v[106:109]
	v_mfma_f32_16x16x32_bf16 v[102:105], v[186:189], v[198:201], v[102:105]
	v_mfma_f32_16x16x32_bf16 v[98:101], v[190:193], v[198:201], v[98:101]
	ds_read_b128 v[198:201], v236 offset:5120
	ds_read_b128 v[242:245], v232 offset:17408
	s_waitcnt lgkmcnt(5)
	v_mfma_f32_16x16x32_bf16 v[94:97], v[178:181], v[202:205], v[94:97]
	v_mfma_f32_16x16x32_bf16 v[90:93], v[182:185], v[202:205], v[90:93]
	v_mfma_f32_16x16x32_bf16 v[86:89], v[186:189], v[202:205], v[86:89]
	v_mfma_f32_16x16x32_bf16 v[82:85], v[190:193], v[202:205], v[82:85]
	ds_read_b128 v[202:205], v236 offset:6144
	ds_read_b128 v[246:249], v232 offset:18432
	s_waitcnt lgkmcnt(6)
	v_mfma_f32_16x16x32_bf16 v[78:81], v[178:181], v[206:209], v[78:81]
	v_mfma_f32_16x16x32_bf16 v[74:77], v[182:185], v[206:209], v[74:77]
	v_mfma_f32_16x16x32_bf16 v[70:73], v[186:189], v[206:209], v[70:73]
	v_mfma_f32_16x16x32_bf16 v[66:69], v[190:193], v[206:209], v[66:69]
	ds_read_b128 v[206:209], v236 offset:7168
	ds_read_b128 v[222:225], v232 offset:19456
	s_sub_i32 s35, s31, s7
	v_add_u32_e32 v235, s35, v235
	v_add_u32_e32 v236, s35, v236
	s_waitcnt lgkmcnt(1)
	s_barrier
; template <int MODE>
; __device__ void gemm_tile2(const u16* __restrict__ X, int lda, const u16* __restrict__ W, int ldb, int K,
;                            int m0, int n0, u16* __restrict__ outb, int vbase,
;                            const float* resid, float* outf, unsigned char* smem) {
;     ...
;   for (int kt2 = 0; kt2 < nk; kt2 += 2) {
; #pragma unroll
;     for (int h = 0; h < 2; ++h) {
;       const int kt = kt2 + h;
;       const u16* st = sbase + h * G2STAGE;
;       bf16x8 fw[4], fx[4];
; #pragma unroll
;       for (int j = 0; j < 4; ++j) fw[j] = *(const bf16x8*)(st + 256 * G2S + (ww * 64 + j * 16 + l15) * G2S + fsw);
; #pragma unroll
;       for (int i = 0; i < 4; ++i) fx[i] = *(const bf16x8*)(st + (wx * 128 + i * 16 + l15) * G2S + fsw);
;       __builtin_amdgcn_sched_barrier(0);
;       __builtin_amdgcn_s_setprio(1);
; #pragma unroll
;       for (int i = 0; i < 4; ++i) {
; #pragma unroll
;         for (int j = 0; j < 4; ++j) {
;           if (MODE == 1) acc[i][j] = mfma16(fx[i], fw[j], acc[i][j]);
;           else acc[i][j] = mfma16(fw[j], fx[i], acc[i][j]);
;         }
;       }
;       __builtin_amdgcn_s_setprio(0);
;       __builtin_amdgcn_sched_barrier(0);
; #pragma unroll
;       for (int i = 0; i < 4; ++i) fx[i] = *(const bf16x8*)(st + (wx * 128 + (i + 4) * 16 + l15) * G2S + fsw);
;       __builtin_amdgcn_sched_barrier(0);
;       if (kt + 1 < nk) G2_LSTORE(1 - h, 1 - h);
;       if (kt + 3 < nk) G2_GLOAD(1 - h, kt + 3);
;       __builtin_amdgcn_sched_barrier(0);
;       __builtin_amdgcn_s_setprio(1);
; #pragma unroll
;       for (int i = 0; i < 4; ++i) {
; #pragma unroll
;         for (int j = 0; j < 4; ++j) {
;           if (MODE == 1) acc[i + 4][j] = mfma16(fx[i], fw[j], acc[i + 4][j]);
;           else acc[i + 4][j] = mfma16(fw[j], fx[i], acc[i + 4][j]);
;         }
;       }
;       __builtin_amdgcn_s_setprio(0);
;       __syncthreads();
;     }
;   }
	s_setprio 1
	v_mfma_f32_16x16x32_bf16 v[62:65], v[178:181], v[194:197], v[62:65]
	v_mfma_f32_16x16x32_bf16 v[58:61], v[182:185], v[194:197], v[58:61]
	v_mfma_f32_16x16x32_bf16 v[54:57], v[186:189], v[194:197], v[54:57]
	v_mfma_f32_16x16x32_bf16 v[50:53], v[190:193], v[194:197], v[50:53]
	ds_read_b128 v[194:197], v237
	v_mfma_f32_16x16x32_bf16 v[46:49], v[178:181], v[198:201], v[46:49]
	v_mfma_f32_16x16x32_bf16 v[42:45], v[182:185], v[198:201], v[42:45]
	v_mfma_f32_16x16x32_bf16 v[38:41], v[186:189], v[198:201], v[38:41]
	v_mfma_f32_16x16x32_bf16 v[34:37], v[190:193], v[198:201], v[34:37]
	ds_read_b128 v[198:201], v237 offset:1024
	v_mfma_f32_16x16x32_bf16 v[30:33], v[178:181], v[202:205], v[30:33]
	v_mfma_f32_16x16x32_bf16 v[26:29], v[182:185], v[202:205], v[26:29]
	v_mfma_f32_16x16x32_bf16 v[22:25], v[186:189], v[202:205], v[22:25]
	v_mfma_f32_16x16x32_bf16 v[18:21], v[190:193], v[202:205], v[18:21]
	ds_read_b128 v[202:205], v237 offset:2048
	v_mfma_f32_16x16x32_bf16 v[14:17], v[178:181], v[206:209], v[14:17]
	v_mfma_f32_16x16x32_bf16 v[10:13], v[182:185], v[206:209], v[10:13]
	v_mfma_f32_16x16x32_bf16 v[6:9], v[186:189], v[206:209], v[6:9]
	v_mfma_f32_16x16x32_bf16 v[2:5], v[190:193], v[206:209], v[2:5]
	ds_read_b128 v[206:209], v237 offset:3072
	s_waitcnt lgkmcnt(3)
	v_mfma_f32_16x16x32_bf16 v[126:129], v[238:241], v[194:197], v[126:129]
	v_mfma_f32_16x16x32_bf16 v[122:125], v[242:245], v[194:197], v[122:125]
	v_mfma_f32_16x16x32_bf16 v[118:121], v[246:249], v[194:197], v[118:121]
	v_mfma_f32_16x16x32_bf16 v[114:117], v[222:225], v[194:197], v[114:117]
	ds_read_b128 v[194:197], v237 offset:4096
	s_waitcnt lgkmcnt(3)
	v_mfma_f32_16x16x32_bf16 v[110:113], v[238:241], v[198:201], v[110:113]
	v_mfma_f32_16x16x32_bf16 v[106:109], v[242:245], v[198:201], v[106:109]
	v_mfma_f32_16x16x32_bf16 v[102:105], v[246:249], v[198:201], v[102:105]
	v_mfma_f32_16x16x32_bf16 v[98:101], v[222:225], v[198:201], v[98:101]
	ds_read_b128 v[198:201], v237 offset:5120
	s_waitcnt lgkmcnt(3)
	v_mfma_f32_16x16x32_bf16 v[94:97], v[238:241], v[202:205], v[94:97]
	v_mfma_f32_16x16x32_bf16 v[90:93], v[242:245], v[202:205], v[90:93]
	v_mfma_f32_16x16x32_bf16 v[86:89], v[246:249], v[202:205], v[86:89]
	v_mfma_f32_16x16x32_bf16 v[82:85], v[222:225], v[202:205], v[82:85]
	ds_read_b128 v[202:205], v237 offset:6144
	s_waitcnt lgkmcnt(3)
	v_mfma_f32_16x16x32_bf16 v[78:81], v[238:241], v[206:209], v[78:81]
	v_mfma_f32_16x16x32_bf16 v[74:77], v[242:245], v[206:209], v[74:77]
	v_mfma_f32_16x16x32_bf16 v[70:73], v[246:249], v[206:209], v[70:73]
	v_mfma_f32_16x16x32_bf16 v[66:69], v[222:225], v[206:209], v[66:69]
	ds_read_b128 v[206:209], v237 offset:7168
	s_sub_i32 s35, s7, s30
	v_add_u32_e32 v232, s35, v232
	v_add_u32_e32 v237, s35, v237
	s_waitcnt lgkmcnt(3)
	v_mfma_f32_16x16x32_bf16 v[62:65], v[238:241], v[194:197], v[62:65]
	v_mfma_f32_16x16x32_bf16 v[58:61], v[242:245], v[194:197], v[58:61]
	v_mfma_f32_16x16x32_bf16 v[54:57], v[246:249], v[194:197], v[54:57]
	v_mfma_f32_16x16x32_bf16 v[50:53], v[222:225], v[194:197], v[50:53]
	s_waitcnt lgkmcnt(2)
	v_mfma_f32_16x16x32_bf16 v[46:49], v[238:241], v[198:201], v[46:49]
	v_mfma_f32_16x16x32_bf16 v[42:45], v[242:245], v[198:201], v[42:45]
	v_mfma_f32_16x16x32_bf16 v[38:41], v[246:249], v[198:201], v[38:41]
	v_mfma_f32_16x16x32_bf16 v[34:37], v[222:225], v[198:201], v[34:37]
	s_waitcnt lgkmcnt(1)
	v_mfma_f32_16x16x32_bf16 v[30:33], v[238:241], v[202:205], v[30:33]
	v_mfma_f32_16x16x32_bf16 v[26:29], v[242:245], v[202:205], v[26:29]
	v_mfma_f32_16x16x32_bf16 v[22:25], v[246:249], v[202:205], v[22:25]
	v_mfma_f32_16x16x32_bf16 v[18:21], v[222:225], v[202:205], v[18:21]
	s_waitcnt lgkmcnt(0)
	v_mfma_f32_16x16x32_bf16 v[14:17], v[238:241], v[206:209], v[14:17]
	v_mfma_f32_16x16x32_bf16 v[10:13], v[242:245], v[206:209], v[10:13]
	v_mfma_f32_16x16x32_bf16 v[6:9], v[246:249], v[206:209], v[6:9]
	v_mfma_f32_16x16x32_bf16 v[2:5], v[222:225], v[206:209], v[2:5]
	s_setprio 0
	s_barrier
	s_mov_b32 s35, s31
	s_mov_b32 s31, s30
	s_mov_b32 s30, s7
	s_mov_b32 s7, s35
	s_nop 7
